# per-MFMA counted waits and reordered fragment reads at both half starts; no second-half prefetch
# speedup vs baseline: 1.0068x; 1.0003x over previous
; #define MFMA16(a, b, c) __builtin_amdgcn_mfma_f32_16x16x32_bf16((a), (b), (c), 0, 0, 0)
;     ...
;   for (int kt = 0; kt < nk; ++kt) {
;     const int buf = kt & 1;
;     const char* cA = smem + buf * STAGE + (wm * 32 * MI + r16) * 128;
;     const char* cB = smem + buf * STAGE + 32768 + (wn * 64 + r16) * 128;
; #pragma unroll
;     for (int k2 = 0; k2 < 2; ++k2) {
;       if (k2 == 1 && kt + 1 < nk) STAGE_TILE(buf ^ 1, (kt + 1) * 64)
;       const int po = ((4 * k2 + q4) ^ swz) * 16;
;       bf16x8 bf[4];
; #pragma unroll
;       for (int nt = 0; nt < 4; ++nt) bf[nt] = *(const bf16x8*)(cB + nt * 16 * 128 + po);
;       bf16x8 afc = *(const bf16x8*)(cA + po);
; #pragma unroll
;       for (int a = 0; a < MT; ++a) {
;         bf16x8 afn = afc;
;         if (a + 1 < MT) afn = *(const bf16x8*)(cA + (a + 1) * 16 * 128 + po);
;         __builtin_amdgcn_sched_barrier(0);
; #pragma unroll
;         for (int nt = 0; nt < 4; ++nt) acc[a][nt] = MFMA16(bf[nt], afc, acc[a][nt]);
;         __builtin_amdgcn_sched_barrier(0);
;         afc = afn;
;       }
;     }
;     asm volatile("s_waitcnt vmcnt(0)" ::: "memory");
;     __syncthreads();
;   }
.LBB0_48:
	s_and_b32 s42, s41, 0x10000
	s_add_i32 s43, s42, 0
	s_xor_b32 s42, s42, 0x10000
	v_add_u32_e32 v174, s43, v147
	v_add_u32_e32 v162, v174, v146
	v_add_u32_e32 v149, s43, v148
	v_add_u32_e32 v175, v149, v146
	ds_read_b128 v[150:153], v162 offset:32768
	ds_read_b128 v[166:169], v175
	ds_read_b128 v[154:157], v162 offset:34816
	ds_read_b128 v[158:161], v162 offset:36864
	ds_read_b128 v[162:165], v162 offset:38912
	ds_read_b128 v[170:173], v175 offset:2048
	s_waitcnt lgkmcnt(4)
	v_mfma_f32_16x16x32_bf16 v[126:129], v[150:153], v[166:169], v[126:129]
	v_readfirstlane_b32 s43, v145
	s_waitcnt lgkmcnt(3)
	v_mfma_f32_16x16x32_bf16 v[122:125], v[154:157], v[166:169], v[122:125]
	s_nop 0
	s_waitcnt lgkmcnt(2)
	v_mfma_f32_16x16x32_bf16 v[118:121], v[158:161], v[166:169], v[118:121]
	s_add_u32 s43, s43, s42
	s_waitcnt lgkmcnt(1)
	v_mfma_f32_16x16x32_bf16 v[114:117], v[162:165], v[166:169], v[114:117]
	ds_read_b128 v[166:169], v175 offset:4096
	s_waitcnt lgkmcnt(1)
	v_mfma_f32_16x16x32_bf16 v[110:113], v[150:153], v[170:173], v[110:113]
	s_add_u32 m0, s43, 0x0
	v_mfma_f32_16x16x32_bf16 v[106:109], v[154:157], v[170:173], v[106:109]
	global_load_lds_dwordx4 v176, s[100:101]
	v_mfma_f32_16x16x32_bf16 v[102:105], v[158:161], v[170:173], v[102:105]
	s_add_u32 m0, s43, 0x2000
	v_mfma_f32_16x16x32_bf16 v[98:101], v[162:165], v[170:173], v[98:101]
	ds_read_b128 v[170:173], v175 offset:6144
	s_waitcnt lgkmcnt(1)
	v_mfma_f32_16x16x32_bf16 v[94:97], v[150:153], v[166:169], v[94:97]
	global_load_lds_dwordx4 v177, s[100:101]
	v_mfma_f32_16x16x32_bf16 v[90:93], v[154:157], v[166:169], v[90:93]
	s_add_u32 m0, s43, 0x4000
	v_mfma_f32_16x16x32_bf16 v[86:89], v[158:161], v[166:169], v[86:89]
	global_load_lds_dwordx4 v178, s[100:101]
	v_mfma_f32_16x16x32_bf16 v[82:85], v[162:165], v[166:169], v[82:85]
	ds_read_b128 v[166:169], v175 offset:8192
	s_waitcnt lgkmcnt(1)
	v_mfma_f32_16x16x32_bf16 v[78:81], v[150:153], v[170:173], v[78:81]
	s_add_u32 m0, s43, 0x6000
	v_mfma_f32_16x16x32_bf16 v[74:77], v[154:157], v[170:173], v[74:77]
	global_load_lds_dwordx4 v179, s[100:101]
	v_mfma_f32_16x16x32_bf16 v[70:73], v[158:161], v[170:173], v[70:73]
	s_add_u32 m0, s43, 0x8000
	v_mfma_f32_16x16x32_bf16 v[66:69], v[162:165], v[170:173], v[66:69]
	ds_read_b128 v[170:173], v175 offset:10240
	s_waitcnt lgkmcnt(1)
	v_mfma_f32_16x16x32_bf16 v[62:65], v[150:153], v[166:169], v[62:65]
	global_load_lds_dwordx4 v180, s[100:101]
	v_mfma_f32_16x16x32_bf16 v[58:61], v[154:157], v[166:169], v[58:61]
	s_add_u32 m0, s43, 0xa000
	v_mfma_f32_16x16x32_bf16 v[54:57], v[158:161], v[166:169], v[54:57]
	global_load_lds_dwordx4 v181, s[100:101]
	v_mfma_f32_16x16x32_bf16 v[50:53], v[162:165], v[166:169], v[50:53]
	ds_read_b128 v[166:169], v175 offset:12288
	s_waitcnt lgkmcnt(1)
	v_mfma_f32_16x16x32_bf16 v[46:49], v[150:153], v[170:173], v[46:49]
	s_add_u32 m0, s43, 0xc000
	v_mfma_f32_16x16x32_bf16 v[42:45], v[154:157], v[170:173], v[42:45]
	global_load_lds_dwordx4 v182, s[100:101]
	v_mfma_f32_16x16x32_bf16 v[38:41], v[158:161], v[170:173], v[38:41]
	s_add_u32 m0, s43, 0xe000
	v_mfma_f32_16x16x32_bf16 v[34:37], v[162:165], v[170:173], v[34:37]
	ds_read_b128 v[170:173], v175 offset:14336
	s_waitcnt lgkmcnt(1)
	v_mfma_f32_16x16x32_bf16 v[30:33], v[150:153], v[166:169], v[30:33]
	global_load_lds_dwordx4 v183, s[100:101]
	v_mfma_f32_16x16x32_bf16 v[26:29], v[154:157], v[166:169], v[26:29]
	v_mfma_f32_16x16x32_bf16 v[22:25], v[158:161], v[166:169], v[22:25]
	v_mfma_f32_16x16x32_bf16 v[18:21], v[162:165], v[166:169], v[18:21]
	s_waitcnt lgkmcnt(0)
	v_mfma_f32_16x16x32_bf16 v[14:17], v[150:153], v[170:173], v[14:17]
	v_mfma_f32_16x16x32_bf16 v[10:13], v[154:157], v[170:173], v[10:13]
	v_mfma_f32_16x16x32_bf16 v[6:9], v[158:161], v[170:173], v[6:9]
	v_mfma_f32_16x16x32_bf16 v[2:5], v[162:165], v[170:173], v[2:5]
	v_add_u32_e32 v162, v174, v144
	v_add_u32_e32 v149, v149, v144
	ds_read_b128 v[150:153], v162 offset:32768
	ds_read_b128 v[166:169], v149
	ds_read_b128 v[154:157], v162 offset:34816
	ds_read_b128 v[158:161], v162 offset:36864
	ds_read_b128 v[162:165], v162 offset:38912
	ds_read_b128 v[170:173], v149 offset:2048
	s_waitcnt lgkmcnt(4)
	v_mfma_f32_16x16x32_bf16 v[126:129], v[150:153], v[166:169], v[126:129]
	s_add_u32 s100, s100, 0x80
	s_waitcnt lgkmcnt(3)
	v_mfma_f32_16x16x32_bf16 v[122:125], v[154:157], v[166:169], v[122:125]
	s_addc_u32 s101, s101, 0
	s_waitcnt lgkmcnt(2)
	v_mfma_f32_16x16x32_bf16 v[118:121], v[158:161], v[166:169], v[118:121]
	s_add_u32 s16, s16, 0x80
	s_waitcnt lgkmcnt(1)
	v_mfma_f32_16x16x32_bf16 v[114:117], v[162:165], v[166:169], v[114:117]
	ds_read_b128 v[166:169], v149 offset:4096
	s_waitcnt lgkmcnt(1)
	v_mfma_f32_16x16x32_bf16 v[110:113], v[150:153], v[170:173], v[110:113]
	s_addc_u32 s17, s17, 0
	v_mfma_f32_16x16x32_bf16 v[106:109], v[154:157], v[170:173], v[106:109]
	s_add_i32 s41, s41, 0x10000
	v_mfma_f32_16x16x32_bf16 v[102:105], v[158:161], v[170:173], v[102:105]
	v_mfma_f32_16x16x32_bf16 v[98:101], v[162:165], v[170:173], v[98:101]
	ds_read_b128 v[170:173], v149 offset:6144
	s_waitcnt lgkmcnt(1)
	v_mfma_f32_16x16x32_bf16 v[94:97], v[150:153], v[166:169], v[94:97]
	v_mfma_f32_16x16x32_bf16 v[90:93], v[154:157], v[166:169], v[90:93]
	v_mfma_f32_16x16x32_bf16 v[86:89], v[158:161], v[166:169], v[86:89]
	v_mfma_f32_16x16x32_bf16 v[82:85], v[162:165], v[166:169], v[82:85]
	ds_read_b128 v[166:169], v149 offset:8192
	s_waitcnt lgkmcnt(1)
	v_mfma_f32_16x16x32_bf16 v[78:81], v[150:153], v[170:173], v[78:81]
	v_mfma_f32_16x16x32_bf16 v[74:77], v[154:157], v[170:173], v[74:77]
	v_mfma_f32_16x16x32_bf16 v[70:73], v[158:161], v[170:173], v[70:73]
	v_mfma_f32_16x16x32_bf16 v[66:69], v[162:165], v[170:173], v[66:69]
	ds_read_b128 v[170:173], v149 offset:10240
	s_waitcnt lgkmcnt(1)
; #define MFMA16(a, b, c) __builtin_amdgcn_mfma_f32_16x16x32_bf16((a), (b), (c), 0, 0, 0)
;     ...
;   for (int kt = 0; kt < nk; ++kt) {
;     const int buf = kt & 1;
;     const char* cA = smem + buf * STAGE + (wm * 32 * MI + r16) * 128;
;     const char* cB = smem + buf * STAGE + 32768 + (wn * 64 + r16) * 128;
; #pragma unroll
;     for (int k2 = 0; k2 < 2; ++k2) {
;       if (k2 == 1 && kt + 1 < nk) STAGE_TILE(buf ^ 1, (kt + 1) * 64)
;       const int po = ((4 * k2 + q4) ^ swz) * 16;
;       bf16x8 bf[4];
; #pragma unroll
;       for (int nt = 0; nt < 4; ++nt) bf[nt] = *(const bf16x8*)(cB + nt * 16 * 128 + po);
;       bf16x8 afc = *(const bf16x8*)(cA + po);
; #pragma unroll
;       for (int a = 0; a < MT; ++a) {
;         bf16x8 afn = afc;
;         if (a + 1 < MT) afn = *(const bf16x8*)(cA + (a + 1) * 16 * 128 + po);
;         __builtin_amdgcn_sched_barrier(0);
; #pragma unroll
;         for (int nt = 0; nt < 4; ++nt) acc[a][nt] = MFMA16(bf[nt], afc, acc[a][nt]);
;         __builtin_amdgcn_sched_barrier(0);
;         afc = afn;
;       }
;     }
;     asm volatile("s_waitcnt vmcnt(0)" ::: "memory");
;     __syncthreads();
;   }
	v_mfma_f32_16x16x32_bf16 v[62:65], v[150:153], v[166:169], v[62:65]
	v_mfma_f32_16x16x32_bf16 v[58:61], v[154:157], v[166:169], v[58:61]
	v_mfma_f32_16x16x32_bf16 v[54:57], v[158:161], v[166:169], v[54:57]
	v_mfma_f32_16x16x32_bf16 v[50:53], v[162:165], v[166:169], v[50:53]
	ds_read_b128 v[166:169], v149 offset:12288
	s_waitcnt lgkmcnt(1)
	v_mfma_f32_16x16x32_bf16 v[46:49], v[150:153], v[170:173], v[46:49]
	v_mfma_f32_16x16x32_bf16 v[42:45], v[154:157], v[170:173], v[42:45]
	v_mfma_f32_16x16x32_bf16 v[38:41], v[158:161], v[170:173], v[38:41]
	v_mfma_f32_16x16x32_bf16 v[34:37], v[162:165], v[170:173], v[34:37]
	ds_read_b128 v[170:173], v149 offset:14336
	s_waitcnt lgkmcnt(1)
	v_mfma_f32_16x16x32_bf16 v[30:33], v[150:153], v[166:169], v[30:33]
	v_mfma_f32_16x16x32_bf16 v[26:29], v[154:157], v[166:169], v[26:29]
	v_mfma_f32_16x16x32_bf16 v[22:25], v[158:161], v[166:169], v[22:25]
	v_mfma_f32_16x16x32_bf16 v[18:21], v[162:165], v[166:169], v[18:21]
	s_waitcnt lgkmcnt(0)
	v_mfma_f32_16x16x32_bf16 v[14:17], v[150:153], v[170:173], v[14:17]
	v_mfma_f32_16x16x32_bf16 v[10:13], v[154:157], v[170:173], v[10:13]
	v_mfma_f32_16x16x32_bf16 v[6:9], v[158:161], v[170:173], v[6:9]
	v_mfma_f32_16x16x32_bf16 v[2:5], v[162:165], v[170:173], v[2:5]
	s_cmpk_eq_i32 s16, 0x1580
	s_waitcnt vmcnt(0)
	s_barrier
	s_cbranch_scc0 .LBB0_48
	s_add_i32 s16, 0, 0x10000
	v_add_u32_e32 v138, s16, v148
	v_readlane_b32 s16, v254, 18
	s_nop 1
	v_add_u32_e32 v139, s16, v147
	v_add_u32_e32 v145, v139, v146
	ds_read_b128 v[130:133], v145
	ds_read_b128 v[134:137], v145 offset:2048
	ds_read_b128 v[148:151], v145 offset:4096
	ds_read_b128 v[152:155], v145 offset:6144
	v_add_u32_e32 v145, v138, v146
	ds_read_b128 v[156:159], v145
	ds_read_b128 v[160:163], v145 offset:2048
	s_waitcnt lgkmcnt(1)
	v_mfma_f32_16x16x32_bf16 v[126:129], v[130:133], v[156:159], v[126:129]
	v_mfma_f32_16x16x32_bf16 v[122:125], v[134:137], v[156:159], v[122:125]
	v_mfma_f32_16x16x32_bf16 v[118:121], v[148:151], v[156:159], v[118:121]
	v_mfma_f32_16x16x32_bf16 v[114:117], v[152:155], v[156:159], v[114:117]
	ds_read_b128 v[156:159], v145 offset:4096
	s_waitcnt lgkmcnt(1)
	v_mfma_f32_16x16x32_bf16 v[110:113], v[130:133], v[160:163], v[110:113]
	v_mfma_f32_16x16x32_bf16 v[106:109], v[134:137], v[160:163], v[106:109]
	v_mfma_f32_16x16x32_bf16 v[102:105], v[148:151], v[160:163], v[102:105]
	v_mfma_f32_16x16x32_bf16 v[98:101], v[152:155], v[160:163], v[98:101]
	ds_read_b128 v[160:163], v145 offset:6144
	s_waitcnt lgkmcnt(1)
	v_mfma_f32_16x16x32_bf16 v[94:97], v[130:133], v[156:159], v[94:97]
	v_mfma_f32_16x16x32_bf16 v[90:93], v[134:137], v[156:159], v[90:93]
	v_mfma_f32_16x16x32_bf16 v[86:89], v[148:151], v[156:159], v[86:89]
	v_mfma_f32_16x16x32_bf16 v[82:85], v[152:155], v[156:159], v[82:85]
	ds_read_b128 v[156:159], v145 offset:8192
	s_waitcnt lgkmcnt(1)
	v_mfma_f32_16x16x32_bf16 v[78:81], v[130:133], v[160:163], v[78:81]
	v_mfma_f32_16x16x32_bf16 v[74:77], v[134:137], v[160:163], v[74:77]
	v_mfma_f32_16x16x32_bf16 v[70:73], v[148:151], v[160:163], v[70:73]
	v_mfma_f32_16x16x32_bf16 v[66:69], v[152:155], v[160:163], v[66:69]
	ds_read_b128 v[160:163], v145 offset:10240
	s_waitcnt lgkmcnt(1)
	v_mfma_f32_16x16x32_bf16 v[62:65], v[130:133], v[156:159], v[62:65]
	v_mfma_f32_16x16x32_bf16 v[58:61], v[134:137], v[156:159], v[58:61]
	v_mfma_f32_16x16x32_bf16 v[54:57], v[148:151], v[156:159], v[54:57]
	v_mfma_f32_16x16x32_bf16 v[50:53], v[152:155], v[156:159], v[50:53]
	ds_read_b128 v[156:159], v145 offset:12288
	s_waitcnt lgkmcnt(1)
	v_mfma_f32_16x16x32_bf16 v[46:49], v[130:133], v[160:163], v[46:49]
	v_mfma_f32_16x16x32_bf16 v[42:45], v[134:137], v[160:163], v[42:45]
	v_mfma_f32_16x16x32_bf16 v[38:41], v[148:151], v[160:163], v[38:41]
	v_mfma_f32_16x16x32_bf16 v[34:37], v[152:155], v[160:163], v[34:37]
	ds_read_b128 v[160:163], v145 offset:14336
	s_waitcnt lgkmcnt(1)
	v_mfma_f32_16x16x32_bf16 v[30:33], v[130:133], v[156:159], v[30:33]
	v_mfma_f32_16x16x32_bf16 v[26:29], v[134:137], v[156:159], v[26:29]
	v_mfma_f32_16x16x32_bf16 v[22:25], v[148:151], v[156:159], v[22:25]
	v_mfma_f32_16x16x32_bf16 v[18:21], v[152:155], v[156:159], v[18:21]
	s_waitcnt lgkmcnt(0)
	v_mfma_f32_16x16x32_bf16 v[14:17], v[130:133], v[160:163], v[14:17]
	v_mfma_f32_16x16x32_bf16 v[10:13], v[134:137], v[160:163], v[10:13]
	v_mfma_f32_16x16x32_bf16 v[6:9], v[148:151], v[160:163], v[6:9]
	v_mfma_f32_16x16x32_bf16 v[2:5], v[152:155], v[160:163], v[2:5]
	v_add_u32_e32 v139, v139, v144
	ds_read_b128 v[130:133], v139
	ds_read_b128 v[134:137], v139 offset:2048
	ds_read_b128 v[146:149], v139 offset:4096
	ds_read_b128 v[150:153], v139 offset:6144
	v_add_u32_e32 v138, v138, v144
	ds_read_b128 v[154:157], v138
	ds_read_b128 v[158:161], v138 offset:2048
	s_waitcnt lgkmcnt(1)
	v_mfma_f32_16x16x32_bf16 v[126:129], v[130:133], v[154:157], v[126:129]
	v_mfma_f32_16x16x32_bf16 v[122:125], v[134:137], v[154:157], v[122:125]
	v_mfma_f32_16x16x32_bf16 v[118:121], v[146:149], v[154:157], v[118:121]
	v_mfma_f32_16x16x32_bf16 v[114:117], v[150:153], v[154:157], v[114:117]
	ds_read_b128 v[154:157], v138 offset:4096
	s_waitcnt lgkmcnt(1)
	v_mfma_f32_16x16x32_bf16 v[110:113], v[130:133], v[158:161], v[110:113]
	v_mfma_f32_16x16x32_bf16 v[106:109], v[134:137], v[158:161], v[106:109]
	v_mfma_f32_16x16x32_bf16 v[102:105], v[146:149], v[158:161], v[102:105]
	v_mfma_f32_16x16x32_bf16 v[98:101], v[150:153], v[158:161], v[98:101]
	ds_read_b128 v[158:161], v138 offset:6144
	s_waitcnt lgkmcnt(1)
	v_mfma_f32_16x16x32_bf16 v[94:97], v[130:133], v[154:157], v[94:97]
	v_mfma_f32_16x16x32_bf16 v[90:93], v[134:137], v[154:157], v[90:93]
	v_mfma_f32_16x16x32_bf16 v[86:89], v[146:149], v[154:157], v[86:89]
	v_mfma_f32_16x16x32_bf16 v[82:85], v[150:153], v[154:157], v[82:85]
	ds_read_b128 v[154:157], v138 offset:8192
	s_waitcnt lgkmcnt(1)
; #define MFMA16(a, b, c) __builtin_amdgcn_mfma_f32_16x16x32_bf16((a), (b), (c), 0, 0, 0)
;     ...
;   for (int kt = 0; kt < nk; ++kt) {
;     const int buf = kt & 1;
;     const char* cA = smem + buf * STAGE + (wm * 32 * MI + r16) * 128;
;     const char* cB = smem + buf * STAGE + 32768 + (wn * 64 + r16) * 128;
; #pragma unroll
;     for (int k2 = 0; k2 < 2; ++k2) {
;       if (k2 == 1 && kt + 1 < nk) STAGE_TILE(buf ^ 1, (kt + 1) * 64)
;       const int po = ((4 * k2 + q4) ^ swz) * 16;
;       bf16x8 bf[4];
; #pragma unroll
;       for (int nt = 0; nt < 4; ++nt) bf[nt] = *(const bf16x8*)(cB + nt * 16 * 128 + po);
;       bf16x8 afc = *(const bf16x8*)(cA + po);
; #pragma unroll
;       for (int a = 0; a < MT; ++a) {
;         bf16x8 afn = afc;
;         if (a + 1 < MT) afn = *(const bf16x8*)(cA + (a + 1) * 16 * 128 + po);
;         __builtin_amdgcn_sched_barrier(0);
; #pragma unroll
;         for (int nt = 0; nt < 4; ++nt) acc[a][nt] = MFMA16(bf[nt], afc, acc[a][nt]);
;         __builtin_amdgcn_sched_barrier(0);
;         afc = afn;
;       }
;     }
;     asm volatile("s_waitcnt vmcnt(0)" ::: "memory");
;     __syncthreads();
;   }
; DI void phase_resid(char* smem, const Params& p, int layer, const bf16_t* A, int K, const bf16_t* W, int gate_idx, bool first) {
;     ...
;   auto ep = [&](int row, int col, float v0, float v1, float v2, float v3) {
;     const int b = row / TT, t = row - b * TT;
;     const float4 g = *(const float4*)(p.mod + (size_t)(layer * 5 + (t < CTXL ? 4 : b)) * 6144 + gate_idx * 1024 + col);
;     const float4 xo = *(const float4*)(xsrc_row(p, first, row) + col);
;     *(float4*)(xdst_row(p, row) + col) = make_float4(xo.x + g.x * v0, xo.y + g.y * v1, xo.z + g.z * v2, xo.w + g.w * v3);
;   };
	v_mfma_f32_16x16x32_bf16 v[78:81], v[130:133], v[158:161], v[78:81]
	v_mfma_f32_16x16x32_bf16 v[74:77], v[134:137], v[158:161], v[74:77]
	v_mfma_f32_16x16x32_bf16 v[70:73], v[146:149], v[158:161], v[70:73]
	v_mfma_f32_16x16x32_bf16 v[66:69], v[150:153], v[158:161], v[66:69]
	ds_read_b128 v[158:161], v138 offset:10240
	s_waitcnt lgkmcnt(1)
	v_mfma_f32_16x16x32_bf16 v[62:65], v[130:133], v[154:157], v[62:65]
	v_mfma_f32_16x16x32_bf16 v[58:61], v[134:137], v[154:157], v[58:61]
	v_mfma_f32_16x16x32_bf16 v[54:57], v[146:149], v[154:157], v[54:57]
	v_mfma_f32_16x16x32_bf16 v[50:53], v[150:153], v[154:157], v[50:53]
	ds_read_b128 v[154:157], v138 offset:12288
	s_waitcnt lgkmcnt(1)
	v_mfma_f32_16x16x32_bf16 v[46:49], v[130:133], v[158:161], v[46:49]
	v_mfma_f32_16x16x32_bf16 v[42:45], v[134:137], v[158:161], v[42:45]
	v_mfma_f32_16x16x32_bf16 v[38:41], v[146:149], v[158:161], v[38:41]
	v_mfma_f32_16x16x32_bf16 v[34:37], v[150:153], v[158:161], v[34:37]
	ds_read_b128 v[158:161], v138 offset:14336
	s_waitcnt lgkmcnt(1)
	v_mfma_f32_16x16x32_bf16 v[30:33], v[130:133], v[154:157], v[30:33]
	v_mfma_f32_16x16x32_bf16 v[26:29], v[134:137], v[154:157], v[26:29]
	v_mfma_f32_16x16x32_bf16 v[22:25], v[146:149], v[154:157], v[22:25]
	v_mfma_f32_16x16x32_bf16 v[18:21], v[150:153], v[154:157], v[18:21]
	s_waitcnt lgkmcnt(0)
	v_mfma_f32_16x16x32_bf16 v[14:17], v[130:133], v[158:161], v[14:17]
	v_mfma_f32_16x16x32_bf16 v[10:13], v[134:137], v[158:161], v[10:13]
	v_mfma_f32_16x16x32_bf16 v[6:9], v[146:149], v[158:161], v[6:9]
	v_mfma_f32_16x16x32_bf16 v[2:5], v[150:153], v[158:161], v[2:5]
	v_or_b32_e32 v131, s40, v142
	v_lshlrev_b32_e32 v130, 6, v143
	v_lshl_add_u32 v142, v140, 7, v131
	v_lshlrev_b32_e32 v131, 2, v141
	v_or3_b32 v134, v130, v131, s39
	v_mul_hi_i32 v130, v142, s1
	v_lshrrev_b32_e32 v131, 31, v130
	v_ashrrev_i32_e32 v130, 11, v130
	v_add_u32_e32 v130, v130, v131
	v_mad_i32_i24 v131, v130, s90, v142
	s_movk_i32 s39, 0x100
	v_cmp_gt_i32_e32 vcc, s39, v131
	v_add_u32_e32 v132, 0xffffff00, v131
	v_ashrrev_i32_e32 v133, 31, v131
	v_readlane_b32 s40, v254, 1
	v_cndmask_b32_e64 v135, v130, 4, vcc
	v_cndmask_b32_e32 v133, 0, v133, vcc
	v_cndmask_b32_e32 v132, v132, v131, vcc
	v_ashrrev_i32_e32 v131, 31, v130
	v_cndmask_b32_e64 v136, 25, 20, vcc
	v_readlane_b32 s41, v254, 2
	v_lshlrev_b64 v[140:141], v136, v[130:131]
	v_lshlrev_b64 v[150:151], 12, v[132:133]
	v_add_u32_e32 v130, s37, v135
	v_mov_b64_e32 v[132:133], s[40:41]
	s_movk_i32 s40, 0x6000
	v_readlane_b32 s42, v254, 3
	v_readlane_b32 s43, v254, 4
	v_mad_i64_i32 v[130:131], s[16:17], v130, s40, v[132:133]
	s_mov_b64 s[42:43], 0x5000
	v_ashrrev_i32_e32 v135, 31, v134
	v_readlane_b32 s16, v252, 26
	v_lshl_add_u64 v[136:137], v[130:131], 0, s[42:43]
	v_lshlrev_b64 v[130:131], 2, v[134:135]
	v_mov_b32_e32 v135, s16
	v_readlane_b32 s16, v252, 28
	s_waitcnt vmcnt(0)
	s_barrier
	s_nop 0
	v_mov_b32_e32 v143, s16
	v_readlane_b32 s16, v252, 25
	v_cndmask_b32_e32 v139, v135, v143, vcc
	s_nop 0
	v_mov_b32_e32 v144, s16
	v_readlane_b32 s16, v252, 27
	v_readlane_b32 s68, v252, 5
	v_readlane_b32 s80, v252, 17
	v_mov_b32_e32 v145, s16
	v_cndmask_b32_e32 v138, v144, v145, vcc
	global_load_dwordx2 v[138:139], v[138:139], off
	v_readlane_b32 s81, v252, 18
	v_readlane_b32 s82, v252, 19
	v_readlane_b32 s83, v252, 20
	v_mov_b32_e32 v146, s81
	v_mov_b32_e32 v148, s80
	v_mov_b32_e32 v147, s83
	v_mov_b32_e32 v149, s82
	v_cndmask_b32_e32 v155, v146, v147, vcc
	v_cndmask_b32_e32 v154, v148, v149, vcc
	v_lshl_add_u64 v[152:153], v[136:137], 0, v[130:131]
	s_add_i32 s38, s38, s30
	s_cmp_gt_i32 s38, 31
	v_readlane_b32 s44, v254, 5
	v_readlane_b32 s45, v254, 6
	v_readlane_b32 s46, v254, 7
	v_readlane_b32 s47, v254, 8
	v_readlane_b32 s48, v254, 9
	v_readlane_b32 s49, v254, 10
	v_readlane_b32 s50, v254, 11
	v_readlane_b32 s51, v254, 12
	v_readlane_b32 s52, v254, 13
	v_readlane_b32 s53, v254, 14
	v_readlane_b32 s54, v254, 15
	v_readlane_b32 s55, v254, 16
	v_readlane_b32 s69, v252, 6
	v_readlane_b32 s70, v252, 7
	v_readlane_b32 s71, v252, 8
	v_readlane_b32 s72, v252, 9
	v_readlane_b32 s73, v252, 10
	v_readlane_b32 s74, v252, 11
	v_readlane_b32 s75, v252, 12
	v_readlane_b32 s76, v252, 13
	v_readlane_b32 s77, v252, 14
	v_readlane_b32 s78, v252, 15
	v_readlane_b32 s79, v252, 16
	s_waitcnt vmcnt(0)
	v_lshl_add_u64 v[138:139], v[138:139], 0, v[140:141]
	v_lshl_add_u64 v[138:139], v[138:139], 0, v[150:151]
	v_lshl_add_u64 v[140:141], v[154:155], 0, v[140:141]
	v_lshl_add_u64 v[138:139], v[138:139], 0, v[130:131]
	v_lshl_add_u64 v[140:141], v[140:141], 0, v[150:151]
	v_lshl_add_u64 v[140:141], v[140:141], 0, v[130:131]
	s_cselect_b64 s[16:17], -1, 0
	global_load_dwordx4 v[156:159], v[152:153], off
	global_load_dwordx4 v[160:163], v[152:153], off offset:64
	global_load_dwordx4 v[164:167], v[152:153], off offset:128
	global_load_dwordx4 v[168:171], v[152:153], off offset:192
	global_load_dwordx4 v[172:175], v[138:139], off
	global_load_dwordx4 v[176:179], v[138:139], off offset:64
	global_load_dwordx4 v[180:183], v[138:139], off offset:128
	global_load_dwordx4 v[184:187], v[138:139], off offset:192
	v_add_co_u32_e32 v138, vcc, 0x10000, v138
	s_nop 1
	v_addc_co_u32_e32 v139, vcc, 0, v139, vcc
	global_load_dwordx4 v[198:201], v[138:139], off
	global_load_dwordx4 v[202:205], v[138:139], off offset:64
	global_load_dwordx4 v[206:209], v[138:139], off offset:128
	global_load_dwordx4 v[210:213], v[138:139], off offset:192
	v_add_co_u32_e32 v138, vcc, 0x10000, v138
	s_nop 1
	v_addc_co_u32_e32 v139, vcc, 0, v139, vcc
	global_load_dwordx4 v[214:217], v[138:139], off
	global_load_dwordx4 v[218:221], v[138:139], off offset:64
	global_load_dwordx4 v[222:225], v[138:139], off offset:128
	global_load_dwordx4 v[142:145], v[138:139], off offset:192
	v_add_co_u32_e32 v138, vcc, 0x10000, v138
	s_nop 1
	v_addc_co_u32_e32 v139, vcc, 0, v139, vcc
	s_waitcnt vmcnt(8)
; DI void phase_resid(char* smem, const Params& p, int layer, const bf16_t* A, int K, const bf16_t* W, int gate_idx, bool first) {
;     ...
;   auto ep = [&](int row, int col, float v0, float v1, float v2, float v3) {
;     const int b = row / TT, t = row - b * TT;
;     const float4 g = *(const float4*)(p.mod + (size_t)(layer * 5 + (t < CTXL ? 4 : b)) * 6144 + gate_idx * 1024 + col);
;     const float4 xo = *(const float4*)(xsrc_row(p, first, row) + col);
;     *(float4*)(xdst_row(p, row) + col) = make_float4(xo.x + g.x * v0, xo.y + g.y * v1, xo.z + g.z * v2, xo.w + g.w * v3);
;   };
	v_pk_fma_f32 v[126:127], v[126:127], v[156:157], v[172:173]
	v_pk_fma_f32 v[128:129], v[128:129], v[158:159], v[174:175]
	v_pk_fma_f32 v[122:123], v[122:123], v[160:161], v[176:177]
	v_pk_fma_f32 v[124:125], v[124:125], v[162:163], v[178:179]
	v_pk_fma_f32 v[118:119], v[118:119], v[164:165], v[180:181]
	v_pk_fma_f32 v[120:121], v[120:121], v[166:167], v[182:183]
	v_pk_fma_f32 v[114:115], v[114:115], v[168:169], v[184:185]
	v_pk_fma_f32 v[116:117], v[116:117], v[170:171], v[186:187]
	global_store_dwordx4 v[140:141], v[126:129], off
	global_store_dwordx4 v[140:141], v[122:125], off offset:64
	global_store_dwordx4 v[140:141], v[118:121], off offset:128
	global_store_dwordx4 v[140:141], v[114:117], off offset:192
	v_add_co_u32_e32 v140, vcc, 0x10000, v140
	s_nop 1
	v_addc_co_u32_e32 v141, vcc, 0, v141, vcc
	global_load_dwordx4 v[172:175], v[138:139], off
	global_load_dwordx4 v[176:179], v[138:139], off offset:64
	global_load_dwordx4 v[180:183], v[138:139], off offset:128
	global_load_dwordx4 v[184:187], v[138:139], off offset:192
	v_add_co_u32_e32 v138, vcc, 0x10000, v138
	s_nop 1
	v_addc_co_u32_e32 v139, vcc, 0, v139, vcc
	s_waitcnt vmcnt(12)
	v_pk_fma_f32 v[110:111], v[110:111], v[156:157], v[198:199]
	v_pk_fma_f32 v[112:113], v[112:113], v[158:159], v[200:201]
	v_pk_fma_f32 v[106:107], v[106:107], v[160:161], v[202:203]
	v_pk_fma_f32 v[108:109], v[108:109], v[162:163], v[204:205]
	v_pk_fma_f32 v[102:103], v[102:103], v[164:165], v[206:207]
	v_pk_fma_f32 v[104:105], v[104:105], v[166:167], v[208:209]
	v_pk_fma_f32 v[98:99], v[98:99], v[168:169], v[210:211]
	v_pk_fma_f32 v[100:101], v[100:101], v[170:171], v[212:213]
	global_store_dwordx4 v[140:141], v[110:113], off
	global_store_dwordx4 v[140:141], v[106:109], off offset:64
	global_store_dwordx4 v[140:141], v[102:105], off offset:128
	global_store_dwordx4 v[140:141], v[98:101], off offset:192
	v_add_co_u32_e32 v140, vcc, 0x10000, v140
	s_nop 1
	v_addc_co_u32_e32 v141, vcc, 0, v141, vcc
	global_load_dwordx4 v[198:201], v[138:139], off
	global_load_dwordx4 v[202:205], v[138:139], off offset:64
	global_load_dwordx4 v[206:209], v[138:139], off offset:128
	global_load_dwordx4 v[210:213], v[138:139], off offset:192
	v_add_co_u32_e32 v138, vcc, 0x10000, v138
	s_nop 1
	v_addc_co_u32_e32 v139, vcc, 0, v139, vcc
	s_waitcnt vmcnt(16)
	v_pk_fma_f32 v[94:95], v[94:95], v[156:157], v[214:215]
	v_pk_fma_f32 v[96:97], v[96:97], v[158:159], v[216:217]
	v_pk_fma_f32 v[90:91], v[90:91], v[160:161], v[218:219]
	v_pk_fma_f32 v[92:93], v[92:93], v[162:163], v[220:221]
	v_pk_fma_f32 v[86:87], v[86:87], v[164:165], v[222:223]
	v_pk_fma_f32 v[88:89], v[88:89], v[166:167], v[224:225]
	v_pk_fma_f32 v[82:83], v[82:83], v[168:169], v[142:143]
	v_pk_fma_f32 v[84:85], v[84:85], v[170:171], v[144:145]
	global_store_dwordx4 v[140:141], v[94:97], off
	global_store_dwordx4 v[140:141], v[90:93], off offset:64
	global_store_dwordx4 v[140:141], v[86:89], off offset:128
	global_store_dwordx4 v[140:141], v[82:85], off offset:192
	v_add_co_u32_e32 v140, vcc, 0x10000, v140
	s_nop 1
	v_addc_co_u32_e32 v141, vcc, 0, v141, vcc
	global_load_dwordx4 v[214:217], v[138:139], off
	global_load_dwordx4 v[218:221], v[138:139], off offset:64
	global_load_dwordx4 v[222:225], v[138:139], off offset:128
	global_load_dwordx4 v[142:145], v[138:139], off offset:192
	v_add_co_u32_e32 v138, vcc, 0x10000, v138
	s_nop 1
	v_addc_co_u32_e32 v139, vcc, 0, v139, vcc
	s_waitcnt vmcnt(16)
; DI void phase_resid(char* smem, const Params& p, int layer, const bf16_t* A, int K, const bf16_t* W, int gate_idx, bool first) {
;     ...
;   auto ep = [&](int row, int col, float v0, float v1, float v2, float v3) {
;     const int b = row / TT, t = row - b * TT;
;     const float4 g = *(const float4*)(p.mod + (size_t)(layer * 5 + (t < CTXL ? 4 : b)) * 6144 + gate_idx * 1024 + col);
;     const float4 xo = *(const float4*)(xsrc_row(p, first, row) + col);
;     *(float4*)(xdst_row(p, row) + col) = make_float4(xo.x + g.x * v0, xo.y + g.y * v1, xo.z + g.z * v2, xo.w + g.w * v3);
;   };
	v_pk_fma_f32 v[78:79], v[78:79], v[156:157], v[172:173]
	v_pk_fma_f32 v[80:81], v[80:81], v[158:159], v[174:175]
	v_pk_fma_f32 v[74:75], v[74:75], v[160:161], v[176:177]
	v_pk_fma_f32 v[76:77], v[76:77], v[162:163], v[178:179]
	v_pk_fma_f32 v[70:71], v[70:71], v[164:165], v[180:181]
	v_pk_fma_f32 v[72:73], v[72:73], v[166:167], v[182:183]
	v_pk_fma_f32 v[66:67], v[66:67], v[168:169], v[184:185]
	v_pk_fma_f32 v[68:69], v[68:69], v[170:171], v[186:187]
	global_store_dwordx4 v[140:141], v[78:81], off
	global_store_dwordx4 v[140:141], v[74:77], off offset:64
	global_store_dwordx4 v[140:141], v[70:73], off offset:128
	global_store_dwordx4 v[140:141], v[66:69], off offset:192
	v_add_co_u32_e32 v140, vcc, 0x10000, v140
	s_nop 1
	v_addc_co_u32_e32 v141, vcc, 0, v141, vcc
	global_load_dwordx4 v[172:175], v[138:139], off
	global_load_dwordx4 v[176:179], v[138:139], off offset:64
	global_load_dwordx4 v[180:183], v[138:139], off offset:128
	global_load_dwordx4 v[184:187], v[138:139], off offset:192
	v_add_co_u32_e32 v138, vcc, 0x10000, v138
	s_nop 1
	v_addc_co_u32_e32 v139, vcc, 0, v139, vcc
	s_waitcnt vmcnt(16)
	v_pk_fma_f32 v[62:63], v[62:63], v[156:157], v[198:199]
	v_pk_fma_f32 v[64:65], v[64:65], v[158:159], v[200:201]
	v_pk_fma_f32 v[58:59], v[58:59], v[160:161], v[202:203]
	v_pk_fma_f32 v[60:61], v[60:61], v[162:163], v[204:205]
	v_pk_fma_f32 v[54:55], v[54:55], v[164:165], v[206:207]
	v_pk_fma_f32 v[56:57], v[56:57], v[166:167], v[208:209]
	v_pk_fma_f32 v[50:51], v[50:51], v[168:169], v[210:211]
	v_pk_fma_f32 v[52:53], v[52:53], v[170:171], v[212:213]
	global_store_dwordx4 v[140:141], v[62:65], off
	global_store_dwordx4 v[140:141], v[58:61], off offset:64
	global_store_dwordx4 v[140:141], v[54:57], off offset:128
	global_store_dwordx4 v[140:141], v[50:53], off offset:192
	v_add_co_u32_e32 v140, vcc, 0x10000, v140
	s_nop 1
	v_addc_co_u32_e32 v141, vcc, 0, v141, vcc
	global_load_dwordx4 v[198:201], v[138:139], off
	global_load_dwordx4 v[202:205], v[138:139], off offset:64
	global_load_dwordx4 v[206:209], v[138:139], off offset:128
	global_load_dwordx4 v[210:213], v[138:139], off offset:192
	s_waitcnt vmcnt(16)
	v_pk_fma_f32 v[46:47], v[46:47], v[156:157], v[214:215]
	v_pk_fma_f32 v[48:49], v[48:49], v[158:159], v[216:217]
	v_pk_fma_f32 v[42:43], v[42:43], v[160:161], v[218:219]
	v_pk_fma_f32 v[44:45], v[44:45], v[162:163], v[220:221]
	v_pk_fma_f32 v[38:39], v[38:39], v[164:165], v[222:223]
	v_pk_fma_f32 v[40:41], v[40:41], v[166:167], v[224:225]
	v_pk_fma_f32 v[34:35], v[34:35], v[168:169], v[142:143]
	v_pk_fma_f32 v[36:37], v[36:37], v[170:171], v[144:145]
	global_store_dwordx4 v[140:141], v[46:49], off
	global_store_dwordx4 v[140:141], v[42:45], off offset:64
	global_store_dwordx4 v[140:141], v[38:41], off offset:128
	global_store_dwordx4 v[140:141], v[34:37], off offset:192
	v_add_co_u32_e32 v140, vcc, 0x10000, v140
	s_nop 1
	v_addc_co_u32_e32 v141, vcc, 0, v141, vcc
	s_waitcnt vmcnt(12)
	v_pk_fma_f32 v[30:31], v[30:31], v[156:157], v[172:173]
	v_pk_fma_f32 v[32:33], v[32:33], v[158:159], v[174:175]
	v_pk_fma_f32 v[26:27], v[26:27], v[160:161], v[176:177]
	v_pk_fma_f32 v[28:29], v[28:29], v[162:163], v[178:179]
	v_pk_fma_f32 v[22:23], v[22:23], v[164:165], v[180:181]
	v_pk_fma_f32 v[24:25], v[24:25], v[166:167], v[182:183]
	v_pk_fma_f32 v[18:19], v[18:19], v[168:169], v[184:185]
	v_pk_fma_f32 v[20:21], v[20:21], v[170:171], v[186:187]
	global_store_dwordx4 v[140:141], v[30:33], off
	global_store_dwordx4 v[140:141], v[26:29], off offset:64
	global_store_dwordx4 v[140:141], v[22:25], off offset:128
	global_store_dwordx4 v[140:141], v[18:21], off offset:192
	v_add_co_u32_e32 v140, vcc, 0x10000, v140
	s_nop 1
	v_addc_co_u32_e32 v141, vcc, 0, v141, vcc
	s_waitcnt vmcnt(8)
	v_pk_fma_f32 v[14:15], v[14:15], v[156:157], v[198:199]
	v_pk_fma_f32 v[16:17], v[16:17], v[158:159], v[200:201]
	v_pk_fma_f32 v[10:11], v[10:11], v[160:161], v[202:203]
	v_pk_fma_f32 v[12:13], v[12:13], v[162:163], v[204:205]
	v_pk_fma_f32 v[6:7], v[6:7], v[164:165], v[206:207]
	v_pk_fma_f32 v[8:9], v[8:9], v[166:167], v[208:209]
	v_pk_fma_f32 v[2:3], v[2:3], v[168:169], v[210:211]
	v_pk_fma_f32 v[4:5], v[4:5], v[170:171], v[212:213]
	global_store_dwordx4 v[140:141], v[14:17], off
	global_store_dwordx4 v[140:141], v[10:13], off offset:64
	global_store_dwordx4 v[140:141], v[6:9], off offset:128
	global_store_dwordx4 v[140:141], v[2:5], off offset:192
	s_branch .LBB0_41

; #define MFMA16(a, b, c) __builtin_amdgcn_mfma_f32_16x16x32_bf16((a), (b), (c), 0, 0, 0)
;     ...
;   for (int kt = 0; kt < nk; ++kt) {
;     const int buf = kt & 1;
;     const char* cA = smem + buf * STAGE + (wm * 32 * MI + r16) * 128;
;     const char* cB = smem + buf * STAGE + 32768 + (wn * 64 + r16) * 128;
; #pragma unroll
;     for (int k2 = 0; k2 < 2; ++k2) {
;       if (k2 == 1 && kt + 1 < nk) STAGE_TILE(buf ^ 1, (kt + 1) * 64)
;       const int po = ((4 * k2 + q4) ^ swz) * 16;
;       bf16x8 bf[4];
; #pragma unroll
;       for (int nt = 0; nt < 4; ++nt) bf[nt] = *(const bf16x8*)(cB + nt * 16 * 128 + po);
;       bf16x8 afc = *(const bf16x8*)(cA + po);
; #pragma unroll
;       for (int a = 0; a < MT; ++a) {
;         bf16x8 afn = afc;
;         if (a + 1 < MT) afn = *(const bf16x8*)(cA + (a + 1) * 16 * 128 + po);
;         __builtin_amdgcn_sched_barrier(0);
; #pragma unroll
;         for (int nt = 0; nt < 4; ++nt) acc[a][nt] = MFMA16(bf[nt], afc, acc[a][nt]);
;         __builtin_amdgcn_sched_barrier(0);
;         afc = afn;
;       }
;     }
;     asm volatile("s_waitcnt vmcnt(0)" ::: "memory");
;     __syncthreads();
;   }
.LBB0_75:
	s_and_b32 s41, s40, 0x10000
	s_add_i32 s42, s41, 0
	v_add_u32_e32 v190, s42, v147
	v_add_u32_e32 v162, v190, v146
	v_add_u32_e32 v149, s42, v148
	v_add_u32_e32 v202, v149, v146
	s_xor_b32 s41, s41, 0x10000
	ds_read_b128 v[150:153], v162 offset:32768
	ds_read_b128 v[166:169], v202
	ds_read_b128 v[154:157], v162 offset:34816
	ds_read_b128 v[158:161], v162 offset:36864
	ds_read_b128 v[162:165], v162 offset:38912
	ds_read_b128 v[170:173], v202 offset:2048
	s_waitcnt lgkmcnt(4)
	v_mfma_f32_16x16x32_bf16 v[126:129], v[150:153], v[166:169], v[126:129]
	v_readfirstlane_b32 s42, v145
	s_waitcnt lgkmcnt(3)
	v_mfma_f32_16x16x32_bf16 v[122:125], v[154:157], v[166:169], v[122:125]
	s_nop 0
	s_waitcnt lgkmcnt(2)
	v_mfma_f32_16x16x32_bf16 v[118:121], v[158:161], v[166:169], v[118:121]
	s_add_u32 s42, s42, s41
	s_waitcnt lgkmcnt(1)
	v_mfma_f32_16x16x32_bf16 v[114:117], v[162:165], v[166:169], v[114:117]
	ds_read_b128 v[166:169], v202 offset:4096
	s_waitcnt lgkmcnt(1)
	v_mfma_f32_16x16x32_bf16 v[110:113], v[150:153], v[170:173], v[110:113]
	s_add_u32 m0, s42, 0x0
	v_mfma_f32_16x16x32_bf16 v[106:109], v[154:157], v[170:173], v[106:109]
	global_load_lds_dwordx4 v174, s[100:101]
	v_mfma_f32_16x16x32_bf16 v[102:105], v[158:161], v[170:173], v[102:105]
	s_add_u32 m0, s42, 0x2000
	v_mfma_f32_16x16x32_bf16 v[98:101], v[162:165], v[170:173], v[98:101]
	ds_read_b128 v[170:173], v202 offset:6144
	s_waitcnt lgkmcnt(1)
	v_mfma_f32_16x16x32_bf16 v[94:97], v[150:153], v[166:169], v[94:97]
	global_load_lds_dwordx4 v175, s[100:101]
	v_mfma_f32_16x16x32_bf16 v[90:93], v[154:157], v[166:169], v[90:93]
	s_add_u32 m0, s42, 0x4000
	v_mfma_f32_16x16x32_bf16 v[86:89], v[158:161], v[166:169], v[86:89]
	global_load_lds_dwordx4 v176, s[100:101]
	v_mfma_f32_16x16x32_bf16 v[82:85], v[162:165], v[166:169], v[82:85]
	ds_read_b128 v[166:169], v202 offset:8192
	s_waitcnt lgkmcnt(1)
	v_mfma_f32_16x16x32_bf16 v[78:81], v[150:153], v[170:173], v[78:81]
	s_add_u32 m0, s42, 0x6000
	v_mfma_f32_16x16x32_bf16 v[74:77], v[154:157], v[170:173], v[74:77]
	global_load_lds_dwordx4 v177, s[100:101]
	v_mfma_f32_16x16x32_bf16 v[70:73], v[158:161], v[170:173], v[70:73]
	s_add_u32 m0, s42, 0x8000
	v_mfma_f32_16x16x32_bf16 v[66:69], v[162:165], v[170:173], v[66:69]
	ds_read_b128 v[170:173], v202 offset:10240
	s_waitcnt lgkmcnt(1)
	v_mfma_f32_16x16x32_bf16 v[62:65], v[150:153], v[166:169], v[62:65]
	global_load_lds_dwordx4 v178, s[100:101]
	v_mfma_f32_16x16x32_bf16 v[58:61], v[154:157], v[166:169], v[58:61]
	s_add_u32 m0, s42, 0xa000
	v_mfma_f32_16x16x32_bf16 v[54:57], v[158:161], v[166:169], v[54:57]
	global_load_lds_dwordx4 v179, s[100:101]
	v_mfma_f32_16x16x32_bf16 v[50:53], v[162:165], v[166:169], v[50:53]
	ds_read_b128 v[166:169], v202 offset:12288
	s_waitcnt lgkmcnt(1)
	v_mfma_f32_16x16x32_bf16 v[46:49], v[150:153], v[170:173], v[46:49]
	s_add_u32 m0, s42, 0xc000
	v_mfma_f32_16x16x32_bf16 v[42:45], v[154:157], v[170:173], v[42:45]
	global_load_lds_dwordx4 v180, s[100:101]
	v_mfma_f32_16x16x32_bf16 v[38:41], v[158:161], v[170:173], v[38:41]
	s_add_u32 m0, s42, 0xe000
	v_mfma_f32_16x16x32_bf16 v[34:37], v[162:165], v[170:173], v[34:37]
	ds_read_b128 v[170:173], v202 offset:14336
	s_waitcnt lgkmcnt(1)
	v_mfma_f32_16x16x32_bf16 v[30:33], v[150:153], v[166:169], v[30:33]
	global_load_lds_dwordx4 v181, s[100:101]
	v_mfma_f32_16x16x32_bf16 v[26:29], v[154:157], v[166:169], v[26:29]
	v_mfma_f32_16x16x32_bf16 v[22:25], v[158:161], v[166:169], v[22:25]
	v_mfma_f32_16x16x32_bf16 v[18:21], v[162:165], v[166:169], v[18:21]
	s_waitcnt lgkmcnt(0)
	v_mfma_f32_16x16x32_bf16 v[14:17], v[150:153], v[170:173], v[14:17]
	v_mfma_f32_16x16x32_bf16 v[10:13], v[154:157], v[170:173], v[10:13]
	v_mfma_f32_16x16x32_bf16 v[6:9], v[158:161], v[170:173], v[6:9]
	v_mfma_f32_16x16x32_bf16 v[2:5], v[162:165], v[170:173], v[2:5]
	v_add_u32_e32 v162, v190, v144
	v_add_u32_e32 v149, v149, v144
	ds_read_b128 v[150:153], v162 offset:32768
	ds_read_b128 v[166:169], v149
	ds_read_b128 v[154:157], v162 offset:34816
	ds_read_b128 v[158:161], v162 offset:36864
	ds_read_b128 v[162:165], v162 offset:38912
	ds_read_b128 v[170:173], v149 offset:2048
	s_waitcnt lgkmcnt(4)
	v_mfma_f32_16x16x32_bf16 v[126:129], v[150:153], v[166:169], v[126:129]
	s_add_u32 s100, s100, 0x80
	s_waitcnt lgkmcnt(3)
	v_mfma_f32_16x16x32_bf16 v[122:125], v[154:157], v[166:169], v[122:125]
	s_addc_u32 s101, s101, 0
	s_waitcnt lgkmcnt(2)
	v_mfma_f32_16x16x32_bf16 v[118:121], v[158:161], v[166:169], v[118:121]
	s_add_u32 s16, s16, 0x80
	s_waitcnt lgkmcnt(1)
	v_mfma_f32_16x16x32_bf16 v[114:117], v[162:165], v[166:169], v[114:117]
	ds_read_b128 v[166:169], v149 offset:4096
	s_waitcnt lgkmcnt(1)
	v_mfma_f32_16x16x32_bf16 v[110:113], v[150:153], v[170:173], v[110:113]
	s_addc_u32 s17, s17, 0
	v_mfma_f32_16x16x32_bf16 v[106:109], v[154:157], v[170:173], v[106:109]
	s_add_i32 s40, s40, 0x10000
	v_mfma_f32_16x16x32_bf16 v[102:105], v[158:161], v[170:173], v[102:105]
	v_mfma_f32_16x16x32_bf16 v[98:101], v[162:165], v[170:173], v[98:101]
	ds_read_b128 v[170:173], v149 offset:6144
	s_waitcnt lgkmcnt(1)
	v_mfma_f32_16x16x32_bf16 v[94:97], v[150:153], v[166:169], v[94:97]
	v_mfma_f32_16x16x32_bf16 v[90:93], v[154:157], v[166:169], v[90:93]
	v_mfma_f32_16x16x32_bf16 v[86:89], v[158:161], v[166:169], v[86:89]
	v_mfma_f32_16x16x32_bf16 v[82:85], v[162:165], v[166:169], v[82:85]
	ds_read_b128 v[166:169], v149 offset:8192
	s_waitcnt lgkmcnt(1)
	v_mfma_f32_16x16x32_bf16 v[78:81], v[150:153], v[170:173], v[78:81]
	v_mfma_f32_16x16x32_bf16 v[74:77], v[154:157], v[170:173], v[74:77]
	v_mfma_f32_16x16x32_bf16 v[70:73], v[158:161], v[170:173], v[70:73]
	v_mfma_f32_16x16x32_bf16 v[66:69], v[162:165], v[170:173], v[66:69]
	ds_read_b128 v[170:173], v149 offset:10240
	s_waitcnt lgkmcnt(1)
; #define MFMA16(a, b, c) __builtin_amdgcn_mfma_f32_16x16x32_bf16((a), (b), (c), 0, 0, 0)
;     ...
;   for (int kt = 0; kt < nk; ++kt) {
;     const int buf = kt & 1;
;     const char* cA = smem + buf * STAGE + (wm * 32 * MI + r16) * 128;
;     const char* cB = smem + buf * STAGE + 32768 + (wn * 64 + r16) * 128;
; #pragma unroll
;     for (int k2 = 0; k2 < 2; ++k2) {
;       if (k2 == 1 && kt + 1 < nk) STAGE_TILE(buf ^ 1, (kt + 1) * 64)
;       const int po = ((4 * k2 + q4) ^ swz) * 16;
;       bf16x8 bf[4];
; #pragma unroll
;       for (int nt = 0; nt < 4; ++nt) bf[nt] = *(const bf16x8*)(cB + nt * 16 * 128 + po);
;       bf16x8 afc = *(const bf16x8*)(cA + po);
; #pragma unroll
;       for (int a = 0; a < MT; ++a) {
;         bf16x8 afn = afc;
;         if (a + 1 < MT) afn = *(const bf16x8*)(cA + (a + 1) * 16 * 128 + po);
;         __builtin_amdgcn_sched_barrier(0);
; #pragma unroll
;         for (int nt = 0; nt < 4; ++nt) acc[a][nt] = MFMA16(bf[nt], afc, acc[a][nt]);
;         __builtin_amdgcn_sched_barrier(0);
;         afc = afn;
;       }
;     }
;     asm volatile("s_waitcnt vmcnt(0)" ::: "memory");
;     __syncthreads();
;   }
	v_mfma_f32_16x16x32_bf16 v[62:65], v[150:153], v[166:169], v[62:65]
	v_mfma_f32_16x16x32_bf16 v[58:61], v[154:157], v[166:169], v[58:61]
	v_mfma_f32_16x16x32_bf16 v[54:57], v[158:161], v[166:169], v[54:57]
	v_mfma_f32_16x16x32_bf16 v[50:53], v[162:165], v[166:169], v[50:53]
	ds_read_b128 v[166:169], v149 offset:12288
	s_waitcnt lgkmcnt(1)
	v_mfma_f32_16x16x32_bf16 v[46:49], v[150:153], v[170:173], v[46:49]
	v_mfma_f32_16x16x32_bf16 v[42:45], v[154:157], v[170:173], v[42:45]
	v_mfma_f32_16x16x32_bf16 v[38:41], v[158:161], v[170:173], v[38:41]
	v_mfma_f32_16x16x32_bf16 v[34:37], v[162:165], v[170:173], v[34:37]
	ds_read_b128 v[170:173], v149 offset:14336
	s_waitcnt lgkmcnt(1)
	v_mfma_f32_16x16x32_bf16 v[30:33], v[150:153], v[166:169], v[30:33]
	v_mfma_f32_16x16x32_bf16 v[26:29], v[154:157], v[166:169], v[26:29]
	v_mfma_f32_16x16x32_bf16 v[22:25], v[158:161], v[166:169], v[22:25]
	v_mfma_f32_16x16x32_bf16 v[18:21], v[162:165], v[166:169], v[18:21]
	s_waitcnt lgkmcnt(0)
	v_mfma_f32_16x16x32_bf16 v[14:17], v[150:153], v[170:173], v[14:17]
	v_mfma_f32_16x16x32_bf16 v[10:13], v[154:157], v[170:173], v[10:13]
	v_mfma_f32_16x16x32_bf16 v[6:9], v[158:161], v[170:173], v[6:9]
	v_mfma_f32_16x16x32_bf16 v[2:5], v[162:165], v[170:173], v[2:5]
	s_cmpk_lg_i32 s16, 0x780
	s_waitcnt vmcnt(0)
	s_barrier
	s_cbranch_scc1 .LBB0_75
	s_add_i32 s16, 0, 0x10000
	v_add_u32_e32 v138, s16, v148
	v_readlane_b32 s16, v254, 18
	s_nop 1
	v_add_u32_e32 v139, s16, v147
	v_add_u32_e32 v145, v139, v146
	ds_read_b128 v[130:133], v145
	ds_read_b128 v[134:137], v145 offset:2048
	ds_read_b128 v[148:151], v145 offset:4096
	ds_read_b128 v[152:155], v145 offset:6144
	v_add_u32_e32 v145, v138, v146
	ds_read_b128 v[156:159], v145
	ds_read_b128 v[160:163], v145 offset:2048
	s_waitcnt lgkmcnt(1)
	v_mfma_f32_16x16x32_bf16 v[126:129], v[130:133], v[156:159], v[126:129]
	v_mfma_f32_16x16x32_bf16 v[122:125], v[134:137], v[156:159], v[122:125]
	v_mfma_f32_16x16x32_bf16 v[118:121], v[148:151], v[156:159], v[118:121]
	v_mfma_f32_16x16x32_bf16 v[114:117], v[152:155], v[156:159], v[114:117]
	ds_read_b128 v[156:159], v145 offset:4096
	s_waitcnt lgkmcnt(1)
	v_mfma_f32_16x16x32_bf16 v[110:113], v[130:133], v[160:163], v[110:113]
	v_mfma_f32_16x16x32_bf16 v[106:109], v[134:137], v[160:163], v[106:109]
	v_mfma_f32_16x16x32_bf16 v[102:105], v[148:151], v[160:163], v[102:105]
	v_mfma_f32_16x16x32_bf16 v[98:101], v[152:155], v[160:163], v[98:101]
	ds_read_b128 v[160:163], v145 offset:6144
	s_waitcnt lgkmcnt(1)
	v_mfma_f32_16x16x32_bf16 v[94:97], v[130:133], v[156:159], v[94:97]
	v_mfma_f32_16x16x32_bf16 v[90:93], v[134:137], v[156:159], v[90:93]
	v_mfma_f32_16x16x32_bf16 v[86:89], v[148:151], v[156:159], v[86:89]
	v_mfma_f32_16x16x32_bf16 v[82:85], v[152:155], v[156:159], v[82:85]
	ds_read_b128 v[156:159], v145 offset:8192
	s_waitcnt lgkmcnt(1)
	v_mfma_f32_16x16x32_bf16 v[78:81], v[130:133], v[160:163], v[78:81]
	v_mfma_f32_16x16x32_bf16 v[74:77], v[134:137], v[160:163], v[74:77]
	v_mfma_f32_16x16x32_bf16 v[70:73], v[148:151], v[160:163], v[70:73]
	v_mfma_f32_16x16x32_bf16 v[66:69], v[152:155], v[160:163], v[66:69]
	ds_read_b128 v[160:163], v145 offset:10240
	s_waitcnt lgkmcnt(1)
	v_mfma_f32_16x16x32_bf16 v[62:65], v[130:133], v[156:159], v[62:65]
	v_mfma_f32_16x16x32_bf16 v[58:61], v[134:137], v[156:159], v[58:61]
	v_mfma_f32_16x16x32_bf16 v[54:57], v[148:151], v[156:159], v[54:57]
	v_mfma_f32_16x16x32_bf16 v[50:53], v[152:155], v[156:159], v[50:53]
	ds_read_b128 v[156:159], v145 offset:12288
	s_waitcnt lgkmcnt(1)
	v_mfma_f32_16x16x32_bf16 v[46:49], v[130:133], v[160:163], v[46:49]
	v_mfma_f32_16x16x32_bf16 v[42:45], v[134:137], v[160:163], v[42:45]
	v_mfma_f32_16x16x32_bf16 v[38:41], v[148:151], v[160:163], v[38:41]
	v_mfma_f32_16x16x32_bf16 v[34:37], v[152:155], v[160:163], v[34:37]
	ds_read_b128 v[160:163], v145 offset:14336
	s_waitcnt lgkmcnt(1)
	v_mfma_f32_16x16x32_bf16 v[30:33], v[130:133], v[156:159], v[30:33]
	v_mfma_f32_16x16x32_bf16 v[26:29], v[134:137], v[156:159], v[26:29]
	v_mfma_f32_16x16x32_bf16 v[22:25], v[148:151], v[156:159], v[22:25]
	v_mfma_f32_16x16x32_bf16 v[18:21], v[152:155], v[156:159], v[18:21]
	s_waitcnt lgkmcnt(0)
	v_mfma_f32_16x16x32_bf16 v[14:17], v[130:133], v[160:163], v[14:17]
	v_mfma_f32_16x16x32_bf16 v[10:13], v[134:137], v[160:163], v[10:13]
	v_mfma_f32_16x16x32_bf16 v[6:9], v[148:151], v[160:163], v[6:9]
	v_mfma_f32_16x16x32_bf16 v[2:5], v[152:155], v[160:163], v[2:5]
	v_add_u32_e32 v139, v139, v144
	ds_read_b128 v[130:133], v139
	ds_read_b128 v[134:137], v139 offset:2048
	ds_read_b128 v[146:149], v139 offset:4096
	ds_read_b128 v[150:153], v139 offset:6144
	v_add_u32_e32 v138, v138, v144
	ds_read_b128 v[154:157], v138
	ds_read_b128 v[158:161], v138 offset:2048
	s_waitcnt lgkmcnt(1)
	v_mfma_f32_16x16x32_bf16 v[126:129], v[130:133], v[154:157], v[126:129]
	v_mfma_f32_16x16x32_bf16 v[122:125], v[134:137], v[154:157], v[122:125]
	v_mfma_f32_16x16x32_bf16 v[118:121], v[146:149], v[154:157], v[118:121]
	v_mfma_f32_16x16x32_bf16 v[114:117], v[150:153], v[154:157], v[114:117]
	ds_read_b128 v[154:157], v138 offset:4096
	s_waitcnt lgkmcnt(1)
	v_mfma_f32_16x16x32_bf16 v[162:165], v[130:133], v[158:161], v[110:113]
	v_mfma_f32_16x16x32_bf16 v[166:169], v[134:137], v[158:161], v[106:109]
	v_mfma_f32_16x16x32_bf16 v[102:105], v[146:149], v[158:161], v[102:105]
	v_mfma_f32_16x16x32_bf16 v[98:101], v[150:153], v[158:161], v[98:101]
	s_nop 0
	ds_read_b128 v[106:109], v138 offset:6144
	s_waitcnt lgkmcnt(1)
	v_mfma_f32_16x16x32_bf16 v[94:97], v[130:133], v[154:157], v[94:97]
	v_mfma_f32_16x16x32_bf16 v[90:93], v[134:137], v[154:157], v[90:93]
	v_mfma_f32_16x16x32_bf16 v[86:89], v[146:149], v[154:157], v[86:89]
	v_mfma_f32_16x16x32_bf16 v[82:85], v[150:153], v[154:157], v[82:85]
	ds_read_b128 v[110:113], v138 offset:8192
	s_waitcnt lgkmcnt(1)
; DI unsigned pack2(float a, float b) { hwf2_t f = {a, b}; return __builtin_bit_cast(unsigned, __builtin_convertvector(f, hwbf2_t)); }
; DI float fsigmoid(float x) { return __builtin_amdgcn_rcpf(1.f + __expf(-x)); }
;     ...
;   const int row0 = m0 + wm * 32 * MI + r16, cbw = n0 + wn * 64;
;   if constexpr (std::is_invocable_v<EP, int, int, int, const f32x4&, const f32x4&, const f32x4&, const f32x4&>) {
; #pragma unroll
;     for (int a = 0; a < MT; ++a) ep(row0 + 16 * a, cbw, q4, acc[a][0], acc[a][1], acc[a][2], acc[a][3]);
; DI void phase_ffn_up(char* smem, const Params& p, int layer) {
;     ...
;   auto ep = [=](int row, int cb, int q4, const f32x4& c0, const f32x4& c1, const f32x4& c2, const f32x4& c3) {
;     const uint4 o = make_uint4(pack2(c0[0] * fsigmoid(c0[0]) * c0[1], c0[2] * fsigmoid(c0[2]) * c0[3]),
;                                pack2(c1[0] * fsigmoid(c1[0]) * c1[1], c1[2] * fsigmoid(c1[2]) * c1[3]),
;                                pack2(c2[0] * fsigmoid(c2[0]) * c2[1], c2[2] * fsigmoid(c2[2]) * c2[3]),
;                                pack2(c3[0] * fsigmoid(c3[0]) * c3[1], c3[2] * fsigmoid(c3[2]) * c3[3]));
;     *(uint4*)(Hh + (size_t)row * FH + (cb >> 1) + q4 * 8) = o;
;   };
	v_mfma_f32_16x16x32_bf16 v[78:81], v[130:133], v[106:109], v[78:81]
	v_mfma_f32_16x16x32_bf16 v[74:77], v[134:137], v[106:109], v[74:77]
	v_mfma_f32_16x16x32_bf16 v[70:73], v[146:149], v[106:109], v[70:73]
	v_mfma_f32_16x16x32_bf16 v[66:69], v[150:153], v[106:109], v[66:69]
	ds_read_b128 v[106:109], v138 offset:10240
	s_waitcnt lgkmcnt(1)
	v_mfma_f32_16x16x32_bf16 v[62:65], v[130:133], v[110:113], v[62:65]
	v_mfma_f32_16x16x32_bf16 v[58:61], v[134:137], v[110:113], v[58:61]
	v_mfma_f32_16x16x32_bf16 v[54:57], v[146:149], v[110:113], v[54:57]
	v_mfma_f32_16x16x32_bf16 v[50:53], v[150:153], v[110:113], v[50:53]
	ds_read_b128 v[110:113], v138 offset:12288
	s_waitcnt lgkmcnt(1)
	v_mfma_f32_16x16x32_bf16 v[46:49], v[130:133], v[106:109], v[46:49]
	v_mfma_f32_16x16x32_bf16 v[42:45], v[134:137], v[106:109], v[42:45]
	v_mfma_f32_16x16x32_bf16 v[38:41], v[146:149], v[106:109], v[38:41]
	v_mfma_f32_16x16x32_bf16 v[34:37], v[150:153], v[106:109], v[34:37]
	ds_read_b128 v[106:109], v138 offset:14336
	s_waitcnt lgkmcnt(1)
	v_mfma_f32_16x16x32_bf16 v[30:33], v[130:133], v[110:113], v[30:33]
	v_mfma_f32_16x16x32_bf16 v[26:29], v[134:137], v[110:113], v[26:29]
	v_mfma_f32_16x16x32_bf16 v[22:25], v[146:149], v[110:113], v[22:25]
	v_mfma_f32_16x16x32_bf16 v[18:21], v[150:153], v[110:113], v[18:21]
	s_waitcnt lgkmcnt(0)
	v_mfma_f32_16x16x32_bf16 v[14:17], v[130:133], v[106:109], v[14:17]
	v_mfma_f32_16x16x32_bf16 v[10:13], v[134:137], v[106:109], v[10:13]
	v_mfma_f32_16x16x32_bf16 v[6:9], v[146:149], v[106:109], v[6:9]
	v_mfma_f32_16x16x32_bf16 v[2:5], v[150:153], v[106:109], v[2:5]
	v_or_b32_e32 v107, s38, v142
	v_lshl_add_u32 v110, v141, 7, v107
	v_mul_f32_e32 v107, 0xbfb8aa3b, v126
	v_mul_f32_e32 v108, 0xbfb8aa3b, v128
	v_exp_f32_e32 v107, v107
	v_exp_f32_e32 v109, v108
	v_lshl_or_b32 v106, v143, 6, s39
	v_ashrrev_i32_e32 v108, 1, v106
	v_add_f32_e32 v106, 1.0, v107
	v_add_f32_e32 v107, 1.0, v109
	v_rcp_f32_e32 v106, v106
	v_rcp_f32_e32 v107, v107
	v_mov_b32_e32 v112, v126
	v_mov_b32_e32 v113, v128
	v_mul_f32_e32 v111, 0xbfb8aa3b, v122
	v_pk_mul_f32 v[106:107], v[112:113], v[106:107]
	v_exp_f32_e32 v111, v111
	v_mul_f32_e32 v112, 0xbfb8aa3b, v124
	v_exp_f32_e32 v113, v112
	v_mov_b32_e32 v128, v127
	v_add_f32_e32 v111, 1.0, v111
	v_rcp_f32_e32 v112, v111
	v_add_f32_e32 v111, 1.0, v113
	v_rcp_f32_e32 v113, v111
	v_pk_mul_f32 v[106:107], v[128:129], v[106:107]
	v_mul_f32_e32 v111, 0xbfb8aa3b, v118
	v_cvt_pk_bf16_f32 v126, v106, v107
	v_mov_b32_e32 v106, v122
	v_mov_b32_e32 v107, v124
	v_pk_mul_f32 v[106:107], v[106:107], v[112:113]
	v_exp_f32_e32 v111, v111
	v_mul_f32_e32 v112, 0xbfb8aa3b, v120
	v_exp_f32_e32 v113, v112
	v_mov_b32_e32 v124, v123
	v_add_f32_e32 v111, 1.0, v111
	v_rcp_f32_e32 v112, v111
	v_add_f32_e32 v111, 1.0, v113
	v_rcp_f32_e32 v113, v111
	v_pk_mul_f32 v[106:107], v[124:125], v[106:107]
	v_mul_f32_e32 v111, 0xbfb8aa3b, v114
	v_cvt_pk_bf16_f32 v127, v106, v107
	v_mov_b32_e32 v106, v118
	v_mov_b32_e32 v107, v120
	v_pk_mul_f32 v[106:107], v[106:107], v[112:113]
	v_exp_f32_e32 v111, v111
	v_mul_f32_e32 v112, 0xbfb8aa3b, v116
	v_exp_f32_e32 v113, v112
	v_mov_b32_e32 v120, v119
	v_add_f32_e32 v111, 1.0, v111
	v_rcp_f32_e32 v112, v111
	v_add_f32_e32 v111, 1.0, v113
	v_rcp_f32_e32 v113, v111
	v_pk_mul_f32 v[106:107], v[120:121], v[106:107]
	v_readlane_b32 s52, v253, 40
	v_cvt_pk_bf16_f32 v128, v106, v107
	v_mov_b32_e32 v106, v114
	v_mov_b32_e32 v107, v116
	v_pk_mul_f32 v[106:107], v[106:107], v[112:113]
	v_mov_b32_e32 v116, v115
	v_mul_f32_e32 v111, 0xbfb8aa3b, v162
	v_pk_mul_f32 v[106:107], v[116:117], v[106:107]
	v_readlane_b32 s54, v253, 42
	v_readlane_b32 s55, v253, 43
	v_exp_f32_e32 v111, v111
	v_mul_f32_e32 v114, 0xbfb8aa3b, v164
	v_ashrrev_i32_e32 v109, 31, v108
	v_cvt_pk_bf16_f32 v129, v106, v107
	v_mov_b64_e32 v[106:107], s[54:55]
	s_movk_i32 s38, 0x1600
	v_exp_f32_e32 v114, v114
	v_mad_i64_i32 v[112:113], s[16:17], v110, s38, v[106:107]
	v_lshlrev_b64 v[108:109], 1, v[108:109]
	v_lshl_add_u64 v[112:113], v[112:113], 0, v[108:109]
	v_lshlrev_b32_e32 v190, 4, v140
	v_lshl_add_u64 v[112:113], v[112:113], 0, v[190:191]
	v_add_f32_e32 v111, 1.0, v111
	s_waitcnt vmcnt(0)
	s_barrier
	global_store_dwordx4 v[112:113], v[126:129], off
	v_rcp_f32_e32 v112, v111
	v_add_f32_e32 v111, 1.0, v114
	v_rcp_f32_e32 v113, v111
	v_mov_b32_e32 v114, v162
	v_mov_b32_e32 v115, v164
	v_mov_b32_e32 v164, v163
	v_pk_mul_f32 v[112:113], v[114:115], v[112:113]
	v_mul_f32_e32 v114, 0xbfb8aa3b, v166
	v_mul_f32_e32 v115, 0xbfb8aa3b, v168
	v_exp_f32_e32 v114, v114
	v_exp_f32_e32 v115, v115
	v_pk_mul_f32 v[112:113], v[164:165], v[112:113]
	v_mov_b32_e32 v116, v166
	v_add_f32_e32 v114, 1.0, v114
	v_add_f32_e32 v115, 1.0, v115
	v_rcp_f32_e32 v114, v114
	v_rcp_f32_e32 v115, v115
	v_cvt_pk_bf16_f32 v112, v112, v113
	v_mov_b32_e32 v117, v168
	v_mul_f32_e32 v113, 0xbfb8aa3b, v102
	v_pk_mul_f32 v[114:115], v[116:117], v[114:115]
	v_exp_f32_e32 v113, v113
	v_mul_f32_e32 v116, 0xbfb8aa3b, v104
	v_exp_f32_e32 v117, v116
	v_mov_b32_e32 v168, v167
	v_add_f32_e32 v113, 1.0, v113
	v_rcp_f32_e32 v116, v113
	v_add_f32_e32 v113, 1.0, v117
	v_rcp_f32_e32 v117, v113
	v_pk_mul_f32 v[114:115], v[168:169], v[114:115]
	v_or_b32_e32 v111, 16, v110
	v_cvt_pk_bf16_f32 v113, v114, v115
	v_mov_b32_e32 v114, v102
	v_mov_b32_e32 v115, v104
	v_mul_f32_e32 v102, 0xbfb8aa3b, v98
	v_pk_mul_f32 v[114:115], v[114:115], v[116:117]
	v_exp_f32_e32 v116, v102
	v_mul_f32_e32 v102, 0xbfb8aa3b, v100
	v_exp_f32_e32 v117, v102
	v_mov_b32_e32 v104, v103
	v_pk_mul_f32 v[102:103], v[104:105], v[114:115]
	v_add_f32_e32 v104, 1.0, v116
	v_add_f32_e32 v105, 1.0, v117
	v_rcp_f32_e32 v104, v104
	v_rcp_f32_e32 v105, v105
; DI unsigned pack2(float a, float b) { hwf2_t f = {a, b}; return __builtin_bit_cast(unsigned, __builtin_convertvector(f, hwbf2_t)); }
; DI float fsigmoid(float x) { return __builtin_amdgcn_rcpf(1.f + __expf(-x)); }
; DI void phase_ffn_up(char* smem, const Params& p, int layer) {
;     ...
;   auto ep = [=](int row, int cb, int q4, const f32x4& c0, const f32x4& c1, const f32x4& c2, const f32x4& c3) {
;     const uint4 o = make_uint4(pack2(c0[0] * fsigmoid(c0[0]) * c0[1], c0[2] * fsigmoid(c0[2]) * c0[3]),
;                                pack2(c1[0] * fsigmoid(c1[0]) * c1[1], c1[2] * fsigmoid(c1[2]) * c1[3]),
;                                pack2(c2[0] * fsigmoid(c2[0]) * c2[1], c2[2] * fsigmoid(c2[2]) * c2[3]),
;                                pack2(c3[0] * fsigmoid(c3[0]) * c3[1], c3[2] * fsigmoid(c3[2]) * c3[3]));
;     *(uint4*)(Hh + (size_t)row * FH + (cb >> 1) + q4 * 8) = o;
;   };
	v_cvt_pk_bf16_f32 v114, v102, v103
	v_mov_b32_e32 v102, v98
	v_mov_b32_e32 v103, v100
	v_pk_mul_f32 v[102:103], v[102:103], v[104:105]
	v_mov_b32_e32 v100, v99
	v_pk_mul_f32 v[98:99], v[100:101], v[102:103]
	v_mul_f32_e32 v100, 0xbfb8aa3b, v94
	v_mul_f32_e32 v101, 0xbfb8aa3b, v96
	v_exp_f32_e32 v100, v100
	v_exp_f32_e32 v101, v101
	v_cvt_pk_bf16_f32 v115, v98, v99
	v_mad_i64_i32 v[98:99], s[16:17], v111, s38, v[106:107]
	v_lshl_add_u64 v[98:99], v[98:99], 0, v[108:109]
	v_lshl_add_u64 v[98:99], v[98:99], 0, v[190:191]
	global_store_dwordx4 v[98:99], v[112:115], off
	v_add_f32_e32 v98, 1.0, v100
	v_add_f32_e32 v99, 1.0, v101
	v_rcp_f32_e32 v98, v98
	v_rcp_f32_e32 v99, v99
	v_mov_b32_e32 v100, v94
	v_mov_b32_e32 v101, v96
	v_mul_f32_e32 v94, 0xbfb8aa3b, v90
	v_pk_mul_f32 v[98:99], v[100:101], v[98:99]
	v_exp_f32_e32 v100, v94
	v_mul_f32_e32 v94, 0xbfb8aa3b, v92
	v_exp_f32_e32 v101, v94
	v_mov_b32_e32 v96, v95
	v_pk_mul_f32 v[94:95], v[96:97], v[98:99]
	v_add_f32_e32 v96, 1.0, v100
	v_add_f32_e32 v97, 1.0, v101
	v_rcp_f32_e32 v96, v96
	v_rcp_f32_e32 v97, v97
	v_mov_b32_e32 v98, v90
	v_mul_f32_e32 v90, 0xbfb8aa3b, v86
	v_cvt_pk_bf16_f32 v94, v94, v95
	v_mov_b32_e32 v99, v92
	v_exp_f32_e32 v95, v90
	v_mul_f32_e32 v90, 0xbfb8aa3b, v88
	v_pk_mul_f32 v[96:97], v[98:99], v[96:97]
	v_exp_f32_e32 v98, v90
	v_mov_b32_e32 v92, v91
	v_pk_mul_f32 v[90:91], v[92:93], v[96:97]
	v_add_f32_e32 v92, 1.0, v95
	v_add_f32_e32 v93, 1.0, v98
	v_rcp_f32_e32 v92, v92
	v_rcp_f32_e32 v93, v93
	v_cvt_pk_bf16_f32 v95, v90, v91
	v_mov_b32_e32 v90, v86
	v_mov_b32_e32 v91, v88
	v_mul_f32_e32 v86, 0xbfb8aa3b, v82
	v_pk_mul_f32 v[90:91], v[90:91], v[92:93]
	v_exp_f32_e32 v92, v86
	v_mul_f32_e32 v86, 0xbfb8aa3b, v84
	v_exp_f32_e32 v93, v86
	v_mov_b32_e32 v88, v87
	v_pk_mul_f32 v[86:87], v[88:89], v[90:91]
	v_add_f32_e32 v88, 1.0, v92
	v_add_f32_e32 v89, 1.0, v93
	v_rcp_f32_e32 v88, v88
	v_rcp_f32_e32 v89, v89
	v_cvt_pk_bf16_f32 v96, v86, v87
	v_mov_b32_e32 v86, v82
	v_mov_b32_e32 v87, v84
	v_pk_mul_f32 v[86:87], v[86:87], v[88:89]
	v_mov_b32_e32 v84, v83
	v_pk_mul_f32 v[82:83], v[84:85], v[86:87]
	v_mul_f32_e32 v84, 0xbfb8aa3b, v78
	v_mul_f32_e32 v85, 0xbfb8aa3b, v80
	v_or_b32_e32 v102, 32, v110
	v_exp_f32_e32 v84, v84
	v_exp_f32_e32 v85, v85
	v_cvt_pk_bf16_f32 v97, v82, v83
	v_mad_i64_i32 v[82:83], s[16:17], v102, s38, v[106:107]
	v_lshl_add_u64 v[82:83], v[82:83], 0, v[108:109]
	v_lshl_add_u64 v[82:83], v[82:83], 0, v[190:191]
	global_store_dwordx4 v[82:83], v[94:97], off
	v_add_f32_e32 v82, 1.0, v84
	v_add_f32_e32 v83, 1.0, v85
	v_rcp_f32_e32 v82, v82
	v_rcp_f32_e32 v83, v83
	v_mov_b32_e32 v84, v78
	v_mov_b32_e32 v85, v80
	v_mul_f32_e32 v78, 0xbfb8aa3b, v74
	v_pk_mul_f32 v[82:83], v[84:85], v[82:83]
	v_exp_f32_e32 v84, v78
	v_mul_f32_e32 v78, 0xbfb8aa3b, v76
	v_exp_f32_e32 v85, v78
	v_mov_b32_e32 v80, v79
	v_pk_mul_f32 v[78:79], v[80:81], v[82:83]
	v_add_f32_e32 v80, 1.0, v84
	v_add_f32_e32 v81, 1.0, v85
	v_rcp_f32_e32 v80, v80
	v_rcp_f32_e32 v81, v81
	v_mov_b32_e32 v82, v74
	v_mul_f32_e32 v74, 0xbfb8aa3b, v70
	v_cvt_pk_bf16_f32 v78, v78, v79
	v_mov_b32_e32 v83, v76
	v_exp_f32_e32 v79, v74
	v_mul_f32_e32 v74, 0xbfb8aa3b, v72
	v_pk_mul_f32 v[80:81], v[82:83], v[80:81]
	v_exp_f32_e32 v82, v74
	v_mov_b32_e32 v76, v75
	v_pk_mul_f32 v[74:75], v[76:77], v[80:81]
	v_add_f32_e32 v76, 1.0, v79
	v_add_f32_e32 v77, 1.0, v82
	v_rcp_f32_e32 v76, v76
	v_rcp_f32_e32 v77, v77
	v_cvt_pk_bf16_f32 v79, v74, v75
	v_mov_b32_e32 v74, v70
	v_mov_b32_e32 v75, v72
	v_mul_f32_e32 v70, 0xbfb8aa3b, v66
	v_pk_mul_f32 v[74:75], v[74:75], v[76:77]
	v_exp_f32_e32 v76, v70
	v_mul_f32_e32 v70, 0xbfb8aa3b, v68
	v_exp_f32_e32 v77, v70
	v_mov_b32_e32 v72, v71
	v_pk_mul_f32 v[70:71], v[72:73], v[74:75]
	v_add_f32_e32 v72, 1.0, v76
	v_add_f32_e32 v73, 1.0, v77
	v_rcp_f32_e32 v72, v72
	v_rcp_f32_e32 v73, v73
	v_cvt_pk_bf16_f32 v80, v70, v71
	v_mov_b32_e32 v70, v66
	v_mov_b32_e32 v71, v68
	v_pk_mul_f32 v[70:71], v[70:71], v[72:73]
	v_mov_b32_e32 v68, v67
	v_pk_mul_f32 v[66:67], v[68:69], v[70:71]
	v_mul_f32_e32 v68, 0xbfb8aa3b, v62
	v_mul_f32_e32 v69, 0xbfb8aa3b, v64
	v_or_b32_e32 v86, 48, v110
	v_exp_f32_e32 v68, v68
	v_exp_f32_e32 v69, v69
	v_cvt_pk_bf16_f32 v81, v66, v67
	v_mad_i64_i32 v[66:67], s[16:17], v86, s38, v[106:107]
	v_lshl_add_u64 v[66:67], v[66:67], 0, v[108:109]
	v_lshl_add_u64 v[66:67], v[66:67], 0, v[190:191]
	global_store_dwordx4 v[66:67], v[78:81], off
	v_add_f32_e32 v66, 1.0, v68
	v_add_f32_e32 v67, 1.0, v69
	v_rcp_f32_e32 v66, v66
	v_rcp_f32_e32 v67, v67
	v_mov_b32_e32 v68, v62
	v_mov_b32_e32 v69, v64
	v_mul_f32_e32 v62, 0xbfb8aa3b, v58
	v_pk_mul_f32 v[66:67], v[68:69], v[66:67]
	v_exp_f32_e32 v68, v62
	v_mul_f32_e32 v62, 0xbfb8aa3b, v60
	v_exp_f32_e32 v69, v62
	v_mov_b32_e32 v64, v63
	v_pk_mul_f32 v[62:63], v[64:65], v[66:67]
	v_add_f32_e32 v64, 1.0, v68
	v_add_f32_e32 v65, 1.0, v69
	v_rcp_f32_e32 v64, v64
	v_rcp_f32_e32 v65, v65
	v_mov_b32_e32 v66, v58
	v_mul_f32_e32 v58, 0xbfb8aa3b, v54
	v_cvt_pk_bf16_f32 v62, v62, v63
	v_mov_b32_e32 v67, v60
	v_exp_f32_e32 v63, v58
	v_mul_f32_e32 v58, 0xbfb8aa3b, v56
	v_pk_mul_f32 v[64:65], v[66:67], v[64:65]
	v_exp_f32_e32 v66, v58
	v_mov_b32_e32 v60, v59
	v_pk_mul_f32 v[58:59], v[60:61], v[64:65]
	v_add_f32_e32 v60, 1.0, v63
	v_add_f32_e32 v61, 1.0, v66
	v_rcp_f32_e32 v60, v60
	v_rcp_f32_e32 v61, v61
	v_cvt_pk_bf16_f32 v63, v58, v59
	v_mov_b32_e32 v58, v54
	v_mov_b32_e32 v59, v56
	v_mul_f32_e32 v54, 0xbfb8aa3b, v50
	v_pk_mul_f32 v[58:59], v[58:59], v[60:61]
	v_exp_f32_e32 v60, v54
	v_mul_f32_e32 v54, 0xbfb8aa3b, v52
	v_exp_f32_e32 v61, v54
	v_mov_b32_e32 v56, v55
	v_pk_mul_f32 v[54:55], v[56:57], v[58:59]
	v_add_f32_e32 v56, 1.0, v60
; DI unsigned pack2(float a, float b) { hwf2_t f = {a, b}; return __builtin_bit_cast(unsigned, __builtin_convertvector(f, hwbf2_t)); }
; DI float fsigmoid(float x) { return __builtin_amdgcn_rcpf(1.f + __expf(-x)); }
; template <int TMI, class F>
; DI void for_tiles_xcd(int MT, int NT, const F& f) {
;     ...
;     for (int c = x; c * 32 < total_full; c += 8)
;       for (int kk = slot; kk < 32; kk += nslots) {
;         const int L = c * 32 + kk;
;         if (L >= total_full) break;
;         int mt, nt; decode(L, mt, nt);
;         f(mt * 256, nt, std::integral_constant<int, 4>{});
; DI void phase_ffn_up(char* smem, const Params& p, int layer) {
;     ...
;   auto ep = [=](int row, int cb, int q4, const f32x4& c0, const f32x4& c1, const f32x4& c2, const f32x4& c3) {
;     const uint4 o = make_uint4(pack2(c0[0] * fsigmoid(c0[0]) * c0[1], c0[2] * fsigmoid(c0[2]) * c0[3]),
;                                pack2(c1[0] * fsigmoid(c1[0]) * c1[1], c1[2] * fsigmoid(c1[2]) * c1[3]),
;                                pack2(c2[0] * fsigmoid(c2[0]) * c2[1], c2[2] * fsigmoid(c2[2]) * c2[3]),
;                                pack2(c3[0] * fsigmoid(c3[0]) * c3[1], c3[2] * fsigmoid(c3[2]) * c3[3]));
;     *(uint4*)(Hh + (size_t)row * FH + (cb >> 1) + q4 * 8) = o;
;   };
	v_add_f32_e32 v57, 1.0, v61
	v_rcp_f32_e32 v56, v56
	v_rcp_f32_e32 v57, v57
	v_cvt_pk_bf16_f32 v64, v54, v55
	v_mov_b32_e32 v54, v50
	v_mov_b32_e32 v55, v52
	v_pk_mul_f32 v[54:55], v[54:55], v[56:57]
	v_mov_b32_e32 v52, v51
	v_pk_mul_f32 v[50:51], v[52:53], v[54:55]
	v_mul_f32_e32 v52, 0xbfb8aa3b, v46
	v_mul_f32_e32 v53, 0xbfb8aa3b, v48
	v_or_b32_e32 v70, 64, v110
	v_exp_f32_e32 v52, v52
	v_exp_f32_e32 v53, v53
	v_cvt_pk_bf16_f32 v65, v50, v51
	v_mad_i64_i32 v[50:51], s[16:17], v70, s38, v[106:107]
	v_lshl_add_u64 v[50:51], v[50:51], 0, v[108:109]
	v_lshl_add_u64 v[50:51], v[50:51], 0, v[190:191]
	global_store_dwordx4 v[50:51], v[62:65], off
	v_add_f32_e32 v50, 1.0, v52
	v_add_f32_e32 v51, 1.0, v53
	v_rcp_f32_e32 v50, v50
	v_rcp_f32_e32 v51, v51
	v_mov_b32_e32 v52, v46
	v_mov_b32_e32 v53, v48
	v_mul_f32_e32 v46, 0xbfb8aa3b, v42
	v_pk_mul_f32 v[50:51], v[52:53], v[50:51]
	v_exp_f32_e32 v52, v46
	v_mul_f32_e32 v46, 0xbfb8aa3b, v44
	v_exp_f32_e32 v53, v46
	v_mov_b32_e32 v48, v47
	v_pk_mul_f32 v[46:47], v[48:49], v[50:51]
	v_add_f32_e32 v48, 1.0, v52
	v_add_f32_e32 v49, 1.0, v53
	v_rcp_f32_e32 v48, v48
	v_rcp_f32_e32 v49, v49
	v_mov_b32_e32 v50, v42
	v_mul_f32_e32 v42, 0xbfb8aa3b, v38
	v_cvt_pk_bf16_f32 v46, v46, v47
	v_mov_b32_e32 v51, v44
	v_exp_f32_e32 v47, v42
	v_mul_f32_e32 v42, 0xbfb8aa3b, v40
	v_pk_mul_f32 v[48:49], v[50:51], v[48:49]
	v_exp_f32_e32 v50, v42
	v_mov_b32_e32 v44, v43
	v_pk_mul_f32 v[42:43], v[44:45], v[48:49]
	v_add_f32_e32 v44, 1.0, v47
	v_add_f32_e32 v45, 1.0, v50
	v_rcp_f32_e32 v44, v44
	v_rcp_f32_e32 v45, v45
	v_cvt_pk_bf16_f32 v47, v42, v43
	v_mov_b32_e32 v42, v38
	v_mov_b32_e32 v43, v40
	v_mul_f32_e32 v38, 0xbfb8aa3b, v34
	v_pk_mul_f32 v[42:43], v[42:43], v[44:45]
	v_exp_f32_e32 v44, v38
	v_mul_f32_e32 v38, 0xbfb8aa3b, v36
	v_exp_f32_e32 v45, v38
	v_mov_b32_e32 v40, v39
	v_pk_mul_f32 v[38:39], v[40:41], v[42:43]
	v_add_f32_e32 v40, 1.0, v44
	v_add_f32_e32 v41, 1.0, v45
	v_rcp_f32_e32 v40, v40
	v_rcp_f32_e32 v41, v41
	v_cvt_pk_bf16_f32 v48, v38, v39
	v_mov_b32_e32 v38, v34
	v_mov_b32_e32 v39, v36
	v_pk_mul_f32 v[38:39], v[38:39], v[40:41]
	v_mov_b32_e32 v36, v35
	v_pk_mul_f32 v[34:35], v[36:37], v[38:39]
	v_mul_f32_e32 v36, 0xbfb8aa3b, v30
	v_mul_f32_e32 v37, 0xbfb8aa3b, v32
	v_or_b32_e32 v54, 0x50, v110
	v_exp_f32_e32 v36, v36
	v_exp_f32_e32 v37, v37
	v_cvt_pk_bf16_f32 v49, v34, v35
	v_mad_i64_i32 v[34:35], s[16:17], v54, s38, v[106:107]
	v_lshl_add_u64 v[34:35], v[34:35], 0, v[108:109]
	v_lshl_add_u64 v[34:35], v[34:35], 0, v[190:191]
	global_store_dwordx4 v[34:35], v[46:49], off
	v_add_f32_e32 v34, 1.0, v36
	v_add_f32_e32 v35, 1.0, v37
	v_rcp_f32_e32 v34, v34
	v_rcp_f32_e32 v35, v35
	v_mov_b32_e32 v36, v30
	v_mov_b32_e32 v37, v32
	v_mul_f32_e32 v30, 0xbfb8aa3b, v26
	v_pk_mul_f32 v[34:35], v[36:37], v[34:35]
	v_exp_f32_e32 v36, v30
	v_mul_f32_e32 v30, 0xbfb8aa3b, v28
	v_exp_f32_e32 v37, v30
	v_mov_b32_e32 v32, v31
	v_pk_mul_f32 v[30:31], v[32:33], v[34:35]
	v_add_f32_e32 v32, 1.0, v36
	v_add_f32_e32 v33, 1.0, v37
	v_rcp_f32_e32 v32, v32
	v_rcp_f32_e32 v33, v33
	v_mov_b32_e32 v34, v26
	v_mul_f32_e32 v26, 0xbfb8aa3b, v22
	v_cvt_pk_bf16_f32 v30, v30, v31
	v_mov_b32_e32 v35, v28
	v_exp_f32_e32 v31, v26
	v_mul_f32_e32 v26, 0xbfb8aa3b, v24
	v_pk_mul_f32 v[32:33], v[34:35], v[32:33]
	v_exp_f32_e32 v34, v26
	v_mov_b32_e32 v28, v27
	v_pk_mul_f32 v[26:27], v[28:29], v[32:33]
	v_add_f32_e32 v28, 1.0, v31
	v_add_f32_e32 v29, 1.0, v34
	v_rcp_f32_e32 v28, v28
	v_rcp_f32_e32 v29, v29
	v_cvt_pk_bf16_f32 v31, v26, v27
	v_mov_b32_e32 v26, v22
	v_mov_b32_e32 v27, v24
	v_mul_f32_e32 v22, 0xbfb8aa3b, v18
	v_pk_mul_f32 v[26:27], v[26:27], v[28:29]
	v_exp_f32_e32 v28, v22
	v_mul_f32_e32 v22, 0xbfb8aa3b, v20
	v_exp_f32_e32 v29, v22
	v_mov_b32_e32 v24, v23
	v_pk_mul_f32 v[22:23], v[24:25], v[26:27]
	v_add_f32_e32 v24, 1.0, v28
	v_add_f32_e32 v25, 1.0, v29
	v_rcp_f32_e32 v24, v24
	v_rcp_f32_e32 v25, v25
	v_cvt_pk_bf16_f32 v32, v22, v23
	v_mov_b32_e32 v22, v18
	v_mov_b32_e32 v23, v20
	v_pk_mul_f32 v[22:23], v[22:23], v[24:25]
	v_mov_b32_e32 v20, v19
	v_pk_mul_f32 v[18:19], v[20:21], v[22:23]
	v_mul_f32_e32 v20, 0xbfb8aa3b, v14
	v_mul_f32_e32 v21, 0xbfb8aa3b, v16
	v_or_b32_e32 v38, 0x60, v110
	v_exp_f32_e32 v20, v20
	v_exp_f32_e32 v21, v21
	v_cvt_pk_bf16_f32 v33, v18, v19
	v_mad_i64_i32 v[18:19], s[16:17], v38, s38, v[106:107]
	v_lshl_add_u64 v[18:19], v[18:19], 0, v[108:109]
	v_lshl_add_u64 v[18:19], v[18:19], 0, v[190:191]
	global_store_dwordx4 v[18:19], v[30:33], off
	v_add_f32_e32 v18, 1.0, v20
	v_add_f32_e32 v19, 1.0, v21
	v_rcp_f32_e32 v18, v18
	v_rcp_f32_e32 v19, v19
	v_mov_b32_e32 v20, v14
	v_mov_b32_e32 v21, v16
	v_mul_f32_e32 v14, 0xbfb8aa3b, v10
	v_pk_mul_f32 v[18:19], v[20:21], v[18:19]
	v_exp_f32_e32 v20, v14
	v_mul_f32_e32 v14, 0xbfb8aa3b, v12
	v_exp_f32_e32 v21, v14
	v_mov_b32_e32 v16, v15
	v_pk_mul_f32 v[14:15], v[16:17], v[18:19]
	v_add_f32_e32 v16, 1.0, v20
	v_add_f32_e32 v17, 1.0, v21
	v_rcp_f32_e32 v16, v16
	v_rcp_f32_e32 v17, v17
	v_mov_b32_e32 v18, v10
	v_mul_f32_e32 v10, 0xbfb8aa3b, v6
	v_cvt_pk_bf16_f32 v14, v14, v15
	v_mov_b32_e32 v19, v12
	v_exp_f32_e32 v15, v10
	v_mul_f32_e32 v10, 0xbfb8aa3b, v8
	v_pk_mul_f32 v[16:17], v[18:19], v[16:17]
	v_exp_f32_e32 v18, v10
	v_mov_b32_e32 v12, v11
	v_pk_mul_f32 v[10:11], v[12:13], v[16:17]
	v_add_f32_e32 v12, 1.0, v15
	v_add_f32_e32 v13, 1.0, v18
	v_rcp_f32_e32 v12, v12
	v_rcp_f32_e32 v13, v13
	v_cvt_pk_bf16_f32 v15, v10, v11
	v_mov_b32_e32 v10, v6
	v_mov_b32_e32 v11, v8
	v_mul_f32_e32 v6, 0xbfb8aa3b, v2
	v_pk_mul_f32 v[10:11], v[10:11], v[12:13]
	v_exp_f32_e32 v12, v6
	v_mul_f32_e32 v6, 0xbfb8aa3b, v4
	v_exp_f32_e32 v13, v6
	v_mov_b32_e32 v8, v7
	v_pk_mul_f32 v[6:7], v[8:9], v[10:11]
	v_add_f32_e32 v8, 1.0, v12
	v_add_f32_e32 v9, 1.0, v13
	v_rcp_f32_e32 v8, v8
	v_rcp_f32_e32 v9, v9
	v_cvt_pk_bf16_f32 v16, v6, v7
	v_mov_b32_e32 v6, v2
	v_mov_b32_e32 v7, v4
	v_pk_mul_f32 v[6:7], v[6:7], v[8:9]
	v_mov_b32_e32 v4, v3
	v_or_b32_e32 v22, 0x70, v110
	v_pk_mul_f32 v[2:3], v[4:5], v[6:7]
	s_add_i32 s37, s37, s30
	v_cvt_pk_bf16_f32 v17, v2, v3
	v_mad_i64_i32 v[2:3], s[16:17], v22, s38, v[106:107]
	v_lshl_add_u64 v[2:3], v[2:3], 0, v[108:109]
	s_cmp_gt_i32 s37, 31
	v_lshl_add_u64 v[2:3], v[2:3], 0, v[190:191]
	s_cselect_b64 s[16:17], -1, 0
	v_readlane_b32 s53, v253, 41
	v_readlane_b32 s56, v253, 44
	v_readlane_b32 s57, v253, 45
	v_readlane_b32 s58, v253, 46
	v_readlane_b32 s59, v253, 47
	v_readlane_b32 s60, v253, 48
	v_readlane_b32 s61, v253, 49
	v_readlane_b32 s62, v253, 50
	v_readlane_b32 s63, v253, 51
	v_readlane_b32 s64, v253, 52
	v_readlane_b32 s65, v253, 53
	v_readlane_b32 s66, v253, 54
	v_readlane_b32 s67, v253, 55
	global_store_dwordx4 v[2:3], v[14:17], off
	s_branch .LBB0_68

; #define MFMA16(a, b, c) __builtin_amdgcn_mfma_f32_16x16x32_bf16((a), (b), (c), 0, 0, 0)
;     ...
;   for (int kt = 0; kt < nk; ++kt) {
;     const int buf = kt & 1;
;     const char* cA = smem + buf * STAGE + (wm * 32 * MI + r16) * 128;
;     const char* cB = smem + buf * STAGE + 32768 + (wn * 64 + r16) * 128;
; #pragma unroll
;     for (int k2 = 0; k2 < 2; ++k2) {
;       if (k2 == 1 && kt + 1 < nk) STAGE_TILE(buf ^ 1, (kt + 1) * 64)
;       const int po = ((4 * k2 + q4) ^ swz) * 16;
;       bf16x8 bf[4];
; #pragma unroll
;       for (int nt = 0; nt < 4; ++nt) bf[nt] = *(const bf16x8*)(cB + nt * 16 * 128 + po);
;       bf16x8 afc = *(const bf16x8*)(cA + po);
; #pragma unroll
;       for (int a = 0; a < MT; ++a) {
;         bf16x8 afn = afc;
;         if (a + 1 < MT) afn = *(const bf16x8*)(cA + (a + 1) * 16 * 128 + po);
;         __builtin_amdgcn_sched_barrier(0);
; #pragma unroll
;         for (int nt = 0; nt < 4; ++nt) acc[a][nt] = MFMA16(bf[nt], afc, acc[a][nt]);
;         __builtin_amdgcn_sched_barrier(0);
;         afc = afn;
;       }
;     }
;     asm volatile("s_waitcnt vmcnt(0)" ::: "memory");
;     __syncthreads();
;   }
.LBB0_107:
	s_and_b32 s46, s45, 0x10000
	s_add_i32 s47, s46, 0
	s_xor_b32 s46, s46, 0x10000
	v_add_u32_e32 v174, s47, v147
	v_add_u32_e32 v162, v174, v146
	v_add_u32_e32 v149, s47, v148
	v_add_u32_e32 v175, v149, v146
	ds_read_b128 v[150:153], v162 offset:32768
	ds_read_b128 v[166:169], v175
	ds_read_b128 v[154:157], v162 offset:34816
	ds_read_b128 v[158:161], v162 offset:36864
	ds_read_b128 v[162:165], v162 offset:38912
	ds_read_b128 v[170:173], v175 offset:2048
	s_waitcnt lgkmcnt(4)
	v_mfma_f32_16x16x32_bf16 v[126:129], v[150:153], v[166:169], v[126:129]
	v_readfirstlane_b32 s47, v145
	s_waitcnt lgkmcnt(3)
	v_mfma_f32_16x16x32_bf16 v[122:125], v[154:157], v[166:169], v[122:125]
	s_nop 0
	s_waitcnt lgkmcnt(2)
	v_mfma_f32_16x16x32_bf16 v[118:121], v[158:161], v[166:169], v[118:121]
	s_add_u32 s47, s47, s46
	s_waitcnt lgkmcnt(1)
	v_mfma_f32_16x16x32_bf16 v[114:117], v[162:165], v[166:169], v[114:117]
	ds_read_b128 v[166:169], v175 offset:4096
	s_waitcnt lgkmcnt(1)
	v_mfma_f32_16x16x32_bf16 v[110:113], v[150:153], v[170:173], v[110:113]
	s_add_u32 m0, s47, 0x0
	v_mfma_f32_16x16x32_bf16 v[106:109], v[154:157], v[170:173], v[106:109]
	global_load_lds_dwordx4 v176, s[100:101]
	v_mfma_f32_16x16x32_bf16 v[102:105], v[158:161], v[170:173], v[102:105]
	s_add_u32 m0, s47, 0x2000
	v_mfma_f32_16x16x32_bf16 v[98:101], v[162:165], v[170:173], v[98:101]
	ds_read_b128 v[170:173], v175 offset:6144
	s_waitcnt lgkmcnt(1)
	v_mfma_f32_16x16x32_bf16 v[94:97], v[150:153], v[166:169], v[94:97]
	global_load_lds_dwordx4 v177, s[100:101]
	v_mfma_f32_16x16x32_bf16 v[90:93], v[154:157], v[166:169], v[90:93]
	s_add_u32 m0, s47, 0x4000
	v_mfma_f32_16x16x32_bf16 v[86:89], v[158:161], v[166:169], v[86:89]
	global_load_lds_dwordx4 v178, s[100:101]
	v_mfma_f32_16x16x32_bf16 v[82:85], v[162:165], v[166:169], v[82:85]
	ds_read_b128 v[166:169], v175 offset:8192
	s_waitcnt lgkmcnt(1)
	v_mfma_f32_16x16x32_bf16 v[78:81], v[150:153], v[170:173], v[78:81]
	s_add_u32 m0, s47, 0x6000
	v_mfma_f32_16x16x32_bf16 v[74:77], v[154:157], v[170:173], v[74:77]
	global_load_lds_dwordx4 v179, s[100:101]
	v_mfma_f32_16x16x32_bf16 v[70:73], v[158:161], v[170:173], v[70:73]
	s_add_u32 m0, s47, 0x8000
	v_mfma_f32_16x16x32_bf16 v[66:69], v[162:165], v[170:173], v[66:69]
	ds_read_b128 v[170:173], v175 offset:10240
	s_waitcnt lgkmcnt(1)
	v_mfma_f32_16x16x32_bf16 v[62:65], v[150:153], v[166:169], v[62:65]
	global_load_lds_dwordx4 v180, s[100:101]
	v_mfma_f32_16x16x32_bf16 v[58:61], v[154:157], v[166:169], v[58:61]
	s_add_u32 m0, s47, 0xa000
	v_mfma_f32_16x16x32_bf16 v[54:57], v[158:161], v[166:169], v[54:57]
	global_load_lds_dwordx4 v181, s[100:101]
	v_mfma_f32_16x16x32_bf16 v[50:53], v[162:165], v[166:169], v[50:53]
	ds_read_b128 v[166:169], v175 offset:12288
	s_waitcnt lgkmcnt(1)
	v_mfma_f32_16x16x32_bf16 v[46:49], v[150:153], v[170:173], v[46:49]
	s_add_u32 m0, s47, 0xc000
	v_mfma_f32_16x16x32_bf16 v[42:45], v[154:157], v[170:173], v[42:45]
	global_load_lds_dwordx4 v182, s[100:101]
	v_mfma_f32_16x16x32_bf16 v[38:41], v[158:161], v[170:173], v[38:41]
	s_add_u32 m0, s47, 0xe000
	v_mfma_f32_16x16x32_bf16 v[34:37], v[162:165], v[170:173], v[34:37]
	ds_read_b128 v[170:173], v175 offset:14336
	s_waitcnt lgkmcnt(1)
	v_mfma_f32_16x16x32_bf16 v[30:33], v[150:153], v[166:169], v[30:33]
	global_load_lds_dwordx4 v183, s[100:101]
	v_mfma_f32_16x16x32_bf16 v[26:29], v[154:157], v[166:169], v[26:29]
	v_mfma_f32_16x16x32_bf16 v[22:25], v[158:161], v[166:169], v[22:25]
	v_mfma_f32_16x16x32_bf16 v[18:21], v[162:165], v[166:169], v[18:21]
	s_waitcnt lgkmcnt(0)
; #define MFMA16(a, b, c) __builtin_amdgcn_mfma_f32_16x16x32_bf16((a), (b), (c), 0, 0, 0)
;     ...
;   for (int kt = 0; kt < nk; ++kt) {
;     const int buf = kt & 1;
;     const char* cA = smem + buf * STAGE + (wm * 32 * MI + r16) * 128;
;     const char* cB = smem + buf * STAGE + 32768 + (wn * 64 + r16) * 128;
; #pragma unroll
;     for (int k2 = 0; k2 < 2; ++k2) {
;       if (k2 == 1 && kt + 1 < nk) STAGE_TILE(buf ^ 1, (kt + 1) * 64)
;       const int po = ((4 * k2 + q4) ^ swz) * 16;
;       bf16x8 bf[4];
; #pragma unroll
;       for (int nt = 0; nt < 4; ++nt) bf[nt] = *(const bf16x8*)(cB + nt * 16 * 128 + po);
;       bf16x8 afc = *(const bf16x8*)(cA + po);
; #pragma unroll
;       for (int a = 0; a < MT; ++a) {
;         bf16x8 afn = afc;
;         if (a + 1 < MT) afn = *(const bf16x8*)(cA + (a + 1) * 16 * 128 + po);
;         __builtin_amdgcn_sched_barrier(0);
; #pragma unroll
;         for (int nt = 0; nt < 4; ++nt) acc[a][nt] = MFMA16(bf[nt], afc, acc[a][nt]);
;         __builtin_amdgcn_sched_barrier(0);
;         afc = afn;
;       }
;     }
;     asm volatile("s_waitcnt vmcnt(0)" ::: "memory");
;     __syncthreads();
;   }
	v_mfma_f32_16x16x32_bf16 v[14:17], v[150:153], v[170:173], v[14:17]
	v_mfma_f32_16x16x32_bf16 v[10:13], v[154:157], v[170:173], v[10:13]
	v_mfma_f32_16x16x32_bf16 v[6:9], v[158:161], v[170:173], v[6:9]
	v_mfma_f32_16x16x32_bf16 v[2:5], v[162:165], v[170:173], v[2:5]
	v_add_u32_e32 v162, v174, v144
	v_add_u32_e32 v149, v149, v144
	ds_read_b128 v[150:153], v162 offset:32768
	ds_read_b128 v[166:169], v149
	ds_read_b128 v[154:157], v162 offset:34816
	ds_read_b128 v[158:161], v162 offset:36864
	ds_read_b128 v[162:165], v162 offset:38912
	ds_read_b128 v[170:173], v149 offset:2048
	s_waitcnt lgkmcnt(4)
	v_mfma_f32_16x16x32_bf16 v[126:129], v[150:153], v[166:169], v[126:129]
	s_add_u32 s100, s100, 0x80
	s_waitcnt lgkmcnt(3)
	v_mfma_f32_16x16x32_bf16 v[122:125], v[154:157], v[166:169], v[122:125]
	s_addc_u32 s101, s101, 0
	s_waitcnt lgkmcnt(2)
	v_mfma_f32_16x16x32_bf16 v[118:121], v[158:161], v[166:169], v[118:121]
	s_add_u32 s22, s22, 0x80
	s_waitcnt lgkmcnt(1)
	v_mfma_f32_16x16x32_bf16 v[114:117], v[162:165], v[166:169], v[114:117]
	ds_read_b128 v[166:169], v149 offset:4096
	s_waitcnt lgkmcnt(1)
	v_mfma_f32_16x16x32_bf16 v[110:113], v[150:153], v[170:173], v[110:113]
	s_addc_u32 s23, s23, 0
	v_mfma_f32_16x16x32_bf16 v[106:109], v[154:157], v[170:173], v[106:109]
	s_add_i32 s45, s45, 0x10000
	v_mfma_f32_16x16x32_bf16 v[102:105], v[158:161], v[170:173], v[102:105]
	v_mfma_f32_16x16x32_bf16 v[98:101], v[162:165], v[170:173], v[98:101]
	ds_read_b128 v[170:173], v149 offset:6144
	s_waitcnt lgkmcnt(1)
	v_mfma_f32_16x16x32_bf16 v[94:97], v[150:153], v[166:169], v[94:97]
	v_mfma_f32_16x16x32_bf16 v[90:93], v[154:157], v[166:169], v[90:93]
	v_mfma_f32_16x16x32_bf16 v[86:89], v[158:161], v[166:169], v[86:89]
	v_mfma_f32_16x16x32_bf16 v[82:85], v[162:165], v[166:169], v[82:85]
	ds_read_b128 v[166:169], v149 offset:8192
	s_waitcnt lgkmcnt(1)
	v_mfma_f32_16x16x32_bf16 v[78:81], v[150:153], v[170:173], v[78:81]
	v_mfma_f32_16x16x32_bf16 v[74:77], v[154:157], v[170:173], v[74:77]
	v_mfma_f32_16x16x32_bf16 v[70:73], v[158:161], v[170:173], v[70:73]
	v_mfma_f32_16x16x32_bf16 v[66:69], v[162:165], v[170:173], v[66:69]
	ds_read_b128 v[170:173], v149 offset:10240
	s_waitcnt lgkmcnt(1)
	v_mfma_f32_16x16x32_bf16 v[62:65], v[150:153], v[166:169], v[62:65]
	v_mfma_f32_16x16x32_bf16 v[58:61], v[154:157], v[166:169], v[58:61]
	v_mfma_f32_16x16x32_bf16 v[54:57], v[158:161], v[166:169], v[54:57]
	v_mfma_f32_16x16x32_bf16 v[50:53], v[162:165], v[166:169], v[50:53]
	ds_read_b128 v[166:169], v149 offset:12288
	s_waitcnt lgkmcnt(1)
	v_mfma_f32_16x16x32_bf16 v[46:49], v[150:153], v[170:173], v[46:49]
	v_mfma_f32_16x16x32_bf16 v[42:45], v[154:157], v[170:173], v[42:45]
	v_mfma_f32_16x16x32_bf16 v[38:41], v[158:161], v[170:173], v[38:41]
	v_mfma_f32_16x16x32_bf16 v[34:37], v[162:165], v[170:173], v[34:37]
	ds_read_b128 v[170:173], v149 offset:14336
	s_waitcnt lgkmcnt(1)
	v_mfma_f32_16x16x32_bf16 v[30:33], v[150:153], v[166:169], v[30:33]
	v_mfma_f32_16x16x32_bf16 v[26:29], v[154:157], v[166:169], v[26:29]
	v_mfma_f32_16x16x32_bf16 v[22:25], v[158:161], v[166:169], v[22:25]
	v_mfma_f32_16x16x32_bf16 v[18:21], v[162:165], v[166:169], v[18:21]
	s_waitcnt lgkmcnt(0)
	v_mfma_f32_16x16x32_bf16 v[14:17], v[150:153], v[170:173], v[14:17]
	v_mfma_f32_16x16x32_bf16 v[10:13], v[154:157], v[170:173], v[10:13]
	v_mfma_f32_16x16x32_bf16 v[6:9], v[158:161], v[170:173], v[6:9]
	v_mfma_f32_16x16x32_bf16 v[2:5], v[162:165], v[170:173], v[2:5]
	s_cmpk_eq_i32 s22, 0x780
	s_waitcnt vmcnt(0)
	s_barrier
	s_cbranch_scc0 .LBB0_107
	s_branch .LBB0_99

; #define MFMA16(a, b, c) __builtin_amdgcn_mfma_f32_16x16x32_bf16((a), (b), (c), 0, 0, 0)
;     ...
;   for (int kt = 0; kt < nk; ++kt) {
;     const int buf = kt & 1;
;     const char* cA = smem + buf * STAGE + (wm * 32 * MI + r16) * 128;
;     const char* cB = smem + buf * STAGE + 32768 + (wn * 64 + r16) * 128;
; #pragma unroll
;     for (int k2 = 0; k2 < 2; ++k2) {
;       if (k2 == 1 && kt + 1 < nk) STAGE_TILE(buf ^ 1, (kt + 1) * 64)
;       const int po = ((4 * k2 + q4) ^ swz) * 16;
;       bf16x8 bf[4];
; #pragma unroll
;       for (int nt = 0; nt < 4; ++nt) bf[nt] = *(const bf16x8*)(cB + nt * 16 * 128 + po);
;       bf16x8 afc = *(const bf16x8*)(cA + po);
; #pragma unroll
;       for (int a = 0; a < MT; ++a) {
;         bf16x8 afn = afc;
;         if (a + 1 < MT) afn = *(const bf16x8*)(cA + (a + 1) * 16 * 128 + po);
;         __builtin_amdgcn_sched_barrier(0);
; #pragma unroll
;         for (int nt = 0; nt < 4; ++nt) acc[a][nt] = MFMA16(bf[nt], afc, acc[a][nt]);
;         __builtin_amdgcn_sched_barrier(0);
;         afc = afn;
;       }
;     }
;     asm volatile("s_waitcnt vmcnt(0)" ::: "memory");
;     __syncthreads();
;   }
.LBB0_565:
	s_and_b32 s6, s5, 0x10000
	s_add_i32 s7, s6, 0
	v_add_u32_e32 v190, s7, v146
	v_add_u32_e32 v164, v190, v145
	v_add_u32_e32 v163, s7, v147
	v_add_u32_e32 v202, v163, v145
	s_xor_b32 s6, s6, 0x10000
	ds_read_b128 v[148:151], v164 offset:32768
	ds_read_b128 v[168:171], v202
	ds_read_b128 v[152:155], v164 offset:34816
	ds_read_b128 v[156:159], v164 offset:36864
	ds_read_b128 v[164:167], v164 offset:38912
	ds_read_b128 v[172:175], v202 offset:2048
	s_waitcnt lgkmcnt(4)
	v_mfma_f32_16x16x32_bf16 v[126:129], v[148:151], v[168:171], v[126:129]
	v_readfirstlane_b32 s7, v144
	s_waitcnt lgkmcnt(3)
	v_mfma_f32_16x16x32_bf16 v[122:125], v[152:155], v[168:171], v[122:125]
	s_nop 0
	s_waitcnt lgkmcnt(2)
	v_mfma_f32_16x16x32_bf16 v[118:121], v[156:159], v[168:171], v[118:121]
	s_add_u32 s7, s7, s6
	s_waitcnt lgkmcnt(1)
	v_mfma_f32_16x16x32_bf16 v[114:117], v[164:167], v[168:171], v[114:117]
	ds_read_b128 v[168:171], v202 offset:4096
	s_waitcnt lgkmcnt(1)
	v_mfma_f32_16x16x32_bf16 v[110:113], v[148:151], v[172:175], v[110:113]
	s_add_u32 m0, s7, 0x0
	v_mfma_f32_16x16x32_bf16 v[106:109], v[152:155], v[172:175], v[106:109]
	global_load_lds_dwordx4 v176, s[100:101]
	v_mfma_f32_16x16x32_bf16 v[102:105], v[156:159], v[172:175], v[102:105]
	s_add_u32 m0, s7, 0x2000
	v_mfma_f32_16x16x32_bf16 v[98:101], v[164:167], v[172:175], v[98:101]
	ds_read_b128 v[172:175], v202 offset:6144
	s_waitcnt lgkmcnt(1)
	v_mfma_f32_16x16x32_bf16 v[94:97], v[148:151], v[168:171], v[94:97]
	global_load_lds_dwordx4 v177, s[100:101]
	v_mfma_f32_16x16x32_bf16 v[90:93], v[152:155], v[168:171], v[90:93]
	s_add_u32 m0, s7, 0x4000
	v_mfma_f32_16x16x32_bf16 v[86:89], v[156:159], v[168:171], v[86:89]
	global_load_lds_dwordx4 v178, s[100:101]
	v_mfma_f32_16x16x32_bf16 v[82:85], v[164:167], v[168:171], v[82:85]
	ds_read_b128 v[168:171], v202 offset:8192
	s_waitcnt lgkmcnt(1)
	v_mfma_f32_16x16x32_bf16 v[78:81], v[148:151], v[172:175], v[78:81]
	s_add_u32 m0, s7, 0x6000
	v_mfma_f32_16x16x32_bf16 v[74:77], v[152:155], v[172:175], v[74:77]
	global_load_lds_dwordx4 v179, s[100:101]
	v_mfma_f32_16x16x32_bf16 v[70:73], v[156:159], v[172:175], v[70:73]
	s_add_u32 m0, s7, 0x8000
	v_mfma_f32_16x16x32_bf16 v[66:69], v[164:167], v[172:175], v[66:69]
	ds_read_b128 v[172:175], v202 offset:10240
	s_waitcnt lgkmcnt(1)
	v_mfma_f32_16x16x32_bf16 v[62:65], v[148:151], v[168:171], v[62:65]
	global_load_lds_dwordx4 v180, s[100:101]
	v_mfma_f32_16x16x32_bf16 v[58:61], v[152:155], v[168:171], v[58:61]
	s_add_u32 m0, s7, 0xa000
	v_mfma_f32_16x16x32_bf16 v[54:57], v[156:159], v[168:171], v[54:57]
	global_load_lds_dwordx4 v181, s[100:101]
	v_mfma_f32_16x16x32_bf16 v[50:53], v[164:167], v[168:171], v[50:53]
	ds_read_b128 v[168:171], v202 offset:12288
	s_waitcnt lgkmcnt(1)
	v_mfma_f32_16x16x32_bf16 v[46:49], v[148:151], v[172:175], v[46:49]
	s_add_u32 m0, s7, 0xc000
	v_mfma_f32_16x16x32_bf16 v[42:45], v[152:155], v[172:175], v[42:45]
	global_load_lds_dwordx4 v182, s[100:101]
	v_mfma_f32_16x16x32_bf16 v[38:41], v[156:159], v[172:175], v[38:41]
	s_add_u32 m0, s7, 0xe000
	v_mfma_f32_16x16x32_bf16 v[34:37], v[164:167], v[172:175], v[34:37]
	ds_read_b128 v[172:175], v202 offset:14336
	s_waitcnt lgkmcnt(1)
	v_mfma_f32_16x16x32_bf16 v[30:33], v[148:151], v[168:171], v[30:33]
	global_load_lds_dwordx4 v183, s[100:101]
	v_mfma_f32_16x16x32_bf16 v[26:29], v[152:155], v[168:171], v[26:29]
	v_mfma_f32_16x16x32_bf16 v[22:25], v[156:159], v[168:171], v[22:25]
	v_mfma_f32_16x16x32_bf16 v[18:21], v[164:167], v[168:171], v[18:21]
	s_waitcnt lgkmcnt(0)
	v_mfma_f32_16x16x32_bf16 v[14:17], v[148:151], v[172:175], v[14:17]
	v_mfma_f32_16x16x32_bf16 v[10:13], v[152:155], v[172:175], v[10:13]
	v_mfma_f32_16x16x32_bf16 v[6:9], v[156:159], v[172:175], v[6:9]
	v_mfma_f32_16x16x32_bf16 v[2:5], v[164:167], v[172:175], v[2:5]
	v_add_u32_e32 v160, v190, v143
	v_add_u32_e32 v161, v163, v143
	ds_read_b128 v[148:151], v160 offset:32768
	ds_read_b128 v[168:171], v161
	ds_read_b128 v[152:155], v160 offset:34816
	ds_read_b128 v[156:159], v160 offset:36864
	ds_read_b128 v[164:167], v160 offset:38912
	ds_read_b128 v[172:175], v161 offset:2048
	s_waitcnt lgkmcnt(4)
	v_mfma_f32_16x16x32_bf16 v[126:129], v[148:151], v[168:171], v[126:129]
	s_add_u32 s100, s100, 0x80
	s_waitcnt lgkmcnt(3)
	v_mfma_f32_16x16x32_bf16 v[122:125], v[152:155], v[168:171], v[122:125]
	s_addc_u32 s101, s101, 0
	s_waitcnt lgkmcnt(2)
	v_mfma_f32_16x16x32_bf16 v[118:121], v[156:159], v[168:171], v[118:121]
	s_add_u32 s2, s2, 0x80
	s_waitcnt lgkmcnt(1)
	v_mfma_f32_16x16x32_bf16 v[114:117], v[164:167], v[168:171], v[114:117]
	ds_read_b128 v[168:171], v161 offset:4096
	s_waitcnt lgkmcnt(1)
	v_mfma_f32_16x16x32_bf16 v[110:113], v[148:151], v[172:175], v[110:113]
	s_addc_u32 s3, s3, 0
	v_mfma_f32_16x16x32_bf16 v[106:109], v[152:155], v[172:175], v[106:109]
	s_add_i32 s5, s5, 0x10000
	v_mfma_f32_16x16x32_bf16 v[102:105], v[156:159], v[172:175], v[102:105]
	v_mfma_f32_16x16x32_bf16 v[98:101], v[164:167], v[172:175], v[98:101]
	ds_read_b128 v[172:175], v161 offset:6144
	s_waitcnt lgkmcnt(1)
	v_mfma_f32_16x16x32_bf16 v[94:97], v[148:151], v[168:171], v[94:97]
	v_mfma_f32_16x16x32_bf16 v[90:93], v[152:155], v[168:171], v[90:93]
	v_mfma_f32_16x16x32_bf16 v[86:89], v[156:159], v[168:171], v[86:89]
	v_mfma_f32_16x16x32_bf16 v[82:85], v[164:167], v[168:171], v[82:85]
	ds_read_b128 v[168:171], v161 offset:8192
	s_waitcnt lgkmcnt(1)
	v_mfma_f32_16x16x32_bf16 v[78:81], v[148:151], v[172:175], v[78:81]
	v_mfma_f32_16x16x32_bf16 v[74:77], v[152:155], v[172:175], v[74:77]
	v_mfma_f32_16x16x32_bf16 v[70:73], v[156:159], v[172:175], v[70:73]
	v_mfma_f32_16x16x32_bf16 v[66:69], v[164:167], v[172:175], v[66:69]
	ds_read_b128 v[172:175], v161 offset:10240
	s_waitcnt lgkmcnt(1)
	v_mfma_f32_16x16x32_bf16 v[62:65], v[148:151], v[168:171], v[62:65]
	v_mfma_f32_16x16x32_bf16 v[58:61], v[152:155], v[168:171], v[58:61]
	v_mfma_f32_16x16x32_bf16 v[54:57], v[156:159], v[168:171], v[54:57]
	v_mfma_f32_16x16x32_bf16 v[50:53], v[164:167], v[168:171], v[50:53]
	ds_read_b128 v[168:171], v161 offset:12288
	s_waitcnt lgkmcnt(1)
	v_mfma_f32_16x16x32_bf16 v[46:49], v[148:151], v[172:175], v[46:49]
	v_mfma_f32_16x16x32_bf16 v[42:45], v[152:155], v[172:175], v[42:45]
	v_mfma_f32_16x16x32_bf16 v[38:41], v[156:159], v[172:175], v[38:41]
	v_mfma_f32_16x16x32_bf16 v[34:37], v[164:167], v[172:175], v[34:37]
	ds_read_b128 v[172:175], v161 offset:14336
	s_waitcnt lgkmcnt(1)
	v_mfma_f32_16x16x32_bf16 v[30:33], v[148:151], v[168:171], v[30:33]
	v_mfma_f32_16x16x32_bf16 v[26:29], v[152:155], v[168:171], v[26:29]
	v_mfma_f32_16x16x32_bf16 v[22:25], v[156:159], v[168:171], v[22:25]
	v_mfma_f32_16x16x32_bf16 v[18:21], v[164:167], v[168:171], v[18:21]
	s_waitcnt lgkmcnt(0)
	v_mfma_f32_16x16x32_bf16 v[14:17], v[148:151], v[172:175], v[14:17]
	v_mfma_f32_16x16x32_bf16 v[10:13], v[152:155], v[172:175], v[10:13]
	v_mfma_f32_16x16x32_bf16 v[6:9], v[156:159], v[172:175], v[6:9]
	v_mfma_f32_16x16x32_bf16 v[2:5], v[164:167], v[172:175], v[2:5]
	s_cmpk_eq_i32 s2, 0x780
	s_waitcnt vmcnt(0)
	s_barrier
; #define MFMA16(a, b, c) __builtin_amdgcn_mfma_f32_16x16x32_bf16((a), (b), (c), 0, 0, 0)
;     ...
;   for (int kt = 0; kt < nk; ++kt) {
;     const int buf = kt & 1;
;     const char* cA = smem + buf * STAGE + (wm * 32 * MI + r16) * 128;
;     const char* cB = smem + buf * STAGE + 32768 + (wn * 64 + r16) * 128;
; #pragma unroll
;     for (int k2 = 0; k2 < 2; ++k2) {
;       if (k2 == 1 && kt + 1 < nk) STAGE_TILE(buf ^ 1, (kt + 1) * 64)
;       const int po = ((4 * k2 + q4) ^ swz) * 16;
;       bf16x8 bf[4];
; #pragma unroll
;       for (int nt = 0; nt < 4; ++nt) bf[nt] = *(const bf16x8*)(cB + nt * 16 * 128 + po);
;       bf16x8 afc = *(const bf16x8*)(cA + po);
; #pragma unroll
;       for (int a = 0; a < MT; ++a) {
;         bf16x8 afn = afc;
;         if (a + 1 < MT) afn = *(const bf16x8*)(cA + (a + 1) * 16 * 128 + po);
;         __builtin_amdgcn_sched_barrier(0);
; #pragma unroll
;         for (int nt = 0; nt < 4; ++nt) acc[a][nt] = MFMA16(bf[nt], afc, acc[a][nt]);
;         __builtin_amdgcn_sched_barrier(0);
;         afc = afn;
;       }
;     }
;     asm volatile("s_waitcnt vmcnt(0)" ::: "memory");
;     __syncthreads();
;   }
; DI void phase_win(char* smem, const Params& p, int layer) {
;     ...
;     if (cbw > 2432) return;
	s_cbranch_scc0 .LBB0_565
	s_add_i32 s2, 0, 0x10000
	v_add_u32_e32 v138, s2, v147
	v_readlane_b32 s2, v254, 18
	s_nop 1
	v_add_u32_e32 v139, s2, v146
	v_add_u32_e32 v144, v139, v145
	ds_read_b128 v[130:133], v144
	ds_read_b128 v[134:137], v144 offset:2048
	ds_read_b128 v[146:149], v144 offset:4096
	ds_read_b128 v[150:153], v144 offset:6144
	v_add_u32_e32 v144, v138, v145
	ds_read_b128 v[154:157], v144
	ds_read_b128 v[158:161], v144 offset:2048
	s_waitcnt lgkmcnt(1)
	v_mfma_f32_16x16x32_bf16 v[122:125], v[134:137], v[154:157], v[122:125]
	v_mfma_f32_16x16x32_bf16 v[118:121], v[146:149], v[154:157], v[118:121]
	v_mfma_f32_16x16x32_bf16 v[114:117], v[150:153], v[154:157], v[114:117]
	v_mfma_f32_16x16x32_bf16 v[126:129], v[130:133], v[154:157], v[126:129]
	ds_read_b128 v[154:157], v144 offset:4096
	s_waitcnt lgkmcnt(1)
	v_mfma_f32_16x16x32_bf16 v[110:113], v[130:133], v[158:161], v[110:113]
	v_mfma_f32_16x16x32_bf16 v[106:109], v[134:137], v[158:161], v[106:109]
	v_mfma_f32_16x16x32_bf16 v[102:105], v[146:149], v[158:161], v[102:105]
	v_mfma_f32_16x16x32_bf16 v[98:101], v[150:153], v[158:161], v[98:101]
	ds_read_b128 v[158:161], v144 offset:6144
	s_waitcnt lgkmcnt(1)
	v_mfma_f32_16x16x32_bf16 v[94:97], v[130:133], v[154:157], v[94:97]
	v_mfma_f32_16x16x32_bf16 v[90:93], v[134:137], v[154:157], v[90:93]
	v_mfma_f32_16x16x32_bf16 v[86:89], v[146:149], v[154:157], v[86:89]
	v_mfma_f32_16x16x32_bf16 v[82:85], v[150:153], v[154:157], v[82:85]
	ds_read_b128 v[154:157], v144 offset:8192
	s_waitcnt lgkmcnt(1)
	v_mfma_f32_16x16x32_bf16 v[78:81], v[130:133], v[158:161], v[78:81]
	v_mfma_f32_16x16x32_bf16 v[74:77], v[134:137], v[158:161], v[74:77]
	v_mfma_f32_16x16x32_bf16 v[70:73], v[146:149], v[158:161], v[70:73]
	v_mfma_f32_16x16x32_bf16 v[66:69], v[150:153], v[158:161], v[66:69]
	ds_read_b128 v[158:161], v144 offset:10240
	s_waitcnt lgkmcnt(1)
	v_mfma_f32_16x16x32_bf16 v[62:65], v[130:133], v[154:157], v[62:65]
	v_mfma_f32_16x16x32_bf16 v[58:61], v[134:137], v[154:157], v[58:61]
	v_mfma_f32_16x16x32_bf16 v[54:57], v[146:149], v[154:157], v[54:57]
	v_mfma_f32_16x16x32_bf16 v[50:53], v[150:153], v[154:157], v[50:53]
	ds_read_b128 v[154:157], v144 offset:12288
	s_waitcnt lgkmcnt(1)
	v_mfma_f32_16x16x32_bf16 v[46:49], v[130:133], v[158:161], v[46:49]
	v_mfma_f32_16x16x32_bf16 v[42:45], v[134:137], v[158:161], v[42:45]
	v_mfma_f32_16x16x32_bf16 v[38:41], v[146:149], v[158:161], v[38:41]
	v_mfma_f32_16x16x32_bf16 v[34:37], v[150:153], v[158:161], v[34:37]
	ds_read_b128 v[158:161], v144 offset:14336
	s_waitcnt lgkmcnt(1)
	v_mfma_f32_16x16x32_bf16 v[30:33], v[130:133], v[154:157], v[30:33]
	v_mfma_f32_16x16x32_bf16 v[26:29], v[134:137], v[154:157], v[26:29]
	v_mfma_f32_16x16x32_bf16 v[22:25], v[146:149], v[154:157], v[22:25]
	v_mfma_f32_16x16x32_bf16 v[18:21], v[150:153], v[154:157], v[18:21]
	s_waitcnt lgkmcnt(0)
	v_mfma_f32_16x16x32_bf16 v[14:17], v[130:133], v[158:161], v[14:17]
	v_mfma_f32_16x16x32_bf16 v[10:13], v[134:137], v[158:161], v[10:13]
	v_mfma_f32_16x16x32_bf16 v[6:9], v[146:149], v[158:161], v[6:9]
	v_mfma_f32_16x16x32_bf16 v[2:5], v[150:153], v[158:161], v[2:5]
	v_add_u32_e32 v130, v139, v143
	ds_read_b128 v[134:137], v130
	ds_read_b128 v[144:147], v130 offset:2048
	ds_read_b128 v[148:151], v130 offset:4096
	ds_read_b128 v[152:155], v130 offset:6144
	v_add_u32_e32 v138, v138, v143
	ds_read_b128 v[156:159], v138
	ds_read_b128 v[164:167], v138 offset:2048
	s_waitcnt lgkmcnt(1)
	v_mfma_f32_16x16x32_bf16 v[130:133], v[134:137], v[156:159], v[126:129]
	v_mfma_f32_16x16x32_bf16 v[122:125], v[144:147], v[156:159], v[122:125]
	v_mfma_f32_16x16x32_bf16 v[118:121], v[148:151], v[156:159], v[118:121]
	v_mfma_f32_16x16x32_bf16 v[114:117], v[152:155], v[156:159], v[114:117]
	ds_read_b128 v[126:129], v138 offset:4096
	s_waitcnt lgkmcnt(1)
	v_mfma_f32_16x16x32_bf16 v[110:113], v[134:137], v[164:167], v[110:113]
	v_mfma_f32_16x16x32_bf16 v[106:109], v[144:147], v[164:167], v[106:109]
	v_mfma_f32_16x16x32_bf16 v[102:105], v[148:151], v[164:167], v[102:105]
	v_mfma_f32_16x16x32_bf16 v[98:101], v[152:155], v[164:167], v[98:101]
	ds_read_b128 v[156:159], v138 offset:6144
	s_waitcnt lgkmcnt(1)
	v_mfma_f32_16x16x32_bf16 v[94:97], v[134:137], v[126:129], v[94:97]
	v_mfma_f32_16x16x32_bf16 v[90:93], v[144:147], v[126:129], v[90:93]
	v_mfma_f32_16x16x32_bf16 v[86:89], v[148:151], v[126:129], v[86:89]
	v_mfma_f32_16x16x32_bf16 v[82:85], v[152:155], v[126:129], v[82:85]
	ds_read_b128 v[126:129], v138 offset:8192
	s_waitcnt lgkmcnt(1)
	v_mfma_f32_16x16x32_bf16 v[78:81], v[134:137], v[156:159], v[78:81]
	v_mfma_f32_16x16x32_bf16 v[74:77], v[144:147], v[156:159], v[74:77]
	v_mfma_f32_16x16x32_bf16 v[70:73], v[148:151], v[156:159], v[70:73]
	v_mfma_f32_16x16x32_bf16 v[66:69], v[152:155], v[156:159], v[66:69]
	ds_read_b128 v[156:159], v138 offset:10240
	s_waitcnt lgkmcnt(1)
	v_mfma_f32_16x16x32_bf16 v[62:65], v[134:137], v[126:129], v[62:65]
	v_mfma_f32_16x16x32_bf16 v[58:61], v[144:147], v[126:129], v[58:61]
	v_mfma_f32_16x16x32_bf16 v[54:57], v[148:151], v[126:129], v[54:57]
	v_mfma_f32_16x16x32_bf16 v[50:53], v[152:155], v[126:129], v[50:53]
	ds_read_b128 v[126:129], v138 offset:12288
	s_waitcnt lgkmcnt(1)
	v_mfma_f32_16x16x32_bf16 v[46:49], v[134:137], v[156:159], v[46:49]
	v_mfma_f32_16x16x32_bf16 v[42:45], v[144:147], v[156:159], v[42:45]
	v_mfma_f32_16x16x32_bf16 v[38:41], v[148:151], v[156:159], v[38:41]
	v_mfma_f32_16x16x32_bf16 v[34:37], v[152:155], v[156:159], v[34:37]
	ds_read_b128 v[156:159], v138 offset:14336
	s_waitcnt lgkmcnt(1)
	v_mfma_f32_16x16x32_bf16 v[30:33], v[134:137], v[126:129], v[30:33]
	v_mfma_f32_16x16x32_bf16 v[26:29], v[144:147], v[126:129], v[26:29]
	v_mfma_f32_16x16x32_bf16 v[22:25], v[148:151], v[126:129], v[22:25]
	v_mfma_f32_16x16x32_bf16 v[18:21], v[152:155], v[126:129], v[18:21]
	s_waitcnt lgkmcnt(0)
	v_mfma_f32_16x16x32_bf16 v[14:17], v[134:137], v[156:159], v[14:17]
	v_mfma_f32_16x16x32_bf16 v[10:13], v[144:147], v[156:159], v[10:13]
	v_mfma_f32_16x16x32_bf16 v[6:9], v[148:151], v[156:159], v[6:9]
	v_mfma_f32_16x16x32_bf16 v[2:5], v[152:155], v[156:159], v[2:5]
	s_waitcnt vmcnt(0)
	v_lshl_or_b32 v190, v142, 6, s22
	s_movk_i32 s2, 0x981
	v_cmp_gt_i32_e32 vcc, s2, v190
	s_barrier
; DI bf16_t f2bf(float x) { return (bf16_t)(pack2(x, 0.f) & 0xffffu); }
; DI void phase_win(char* smem, const Params& p, int layer) {
;     ...
;     if (cbw > 2432) return;
;     const int b = row / TT, t = row - b * TT;
;     const bool lat = t >= CTXL;
;     const int pos = t - CTXL;
;     float v[16] = {c0[0], c0[1], c0[2], c0[3], c1[0], c1[1], c1[2], c1[3], c2[0], c2[1], c2[2], c2[3], c3[0], c3[1], c3[2], c3[3]};
;     if (cbw >= 640 && cbw < 768) {
;       bf16_t* vp = p.VsT + ((size_t)(b * 2 + ((cbw - 640) >> 6)) * 64 + q4 * 16) * TT + t;
; #pragma unroll
;       for (int i = 0; i < 16; ++i) vp[(size_t)i * TT] = f2bf(v[i]);
;       return;
;     }
;     const bool r16 = cbw >= 256 && cbw < 640, rkr = cbw == 2432;
;     if (rkr && q4 >= 2) return;
;     if (lat && (r16 || rkr)) {
;       const int a = r16 ? (q4 >> 1) : q4;
;       const int pa = a ? (pos & 63) : (pos >> 6);
;       const float* tab = r16 ? p.ropeS + 2 * (pa * 16 + (q4 & 1) * 8) : p.ropeM + 2 * (pa * 8);
; #pragma unroll
;       for (int k = 0; k < 4; ++k) {
;         const float4 cs = *(const float4*)(tab + 4 * k);
;         const float x0 = v[4 * k], x1 = v[4 * k + 1], x2 = v[4 * k + 2], x3 = v[4 * k + 3];
;         v[4 * k] = x0 * cs.x - x1 * cs.y; v[4 * k + 1] = x1 * cs.x + x0 * cs.y;
;         v[4 * k + 2] = x2 * cs.z - x3 * cs.w; v[4 * k + 3] = x3 * cs.z + x2 * cs.w;
;       }
;     }
	s_and_saveexec_b64 s[96:97], vcc
	s_cbranch_execz .LBB0_557
	v_or_b32_e32 v126, s4, v162
	v_lshl_add_u32 v136, v141, 7, v126
	v_and_b32_e32 v126, 0xffffff80, v190
	s_movk_i32 s2, 0x280
	v_cmp_ne_u32_e64 s[16:17], s2, v126
	s_movk_i32 s2, 0x27f
	v_cmp_lt_i32_e64 s[4:5], s2, v190
	s_movk_i32 s2, 0x980
	v_cmp_ne_u32_e64 s[8:9], s2, v190
	v_cmp_gt_u32_e64 s[6:7], 2, v140
	v_add_u32_e32 v126, 0xffffff00, v190
	v_cmp_eq_u32_e32 vcc, s2, v190
	s_or_b64 s[2:3], s[8:9], s[6:7]
	s_movk_i32 s6, 0x180
	v_cmp_gt_u32_e64 s[12:13], s6, v126
	s_or_b64 s[86:87], vcc, s[12:13]
	v_lshrrev_b32_e32 v160, 6, v126
	v_cndmask_b32_e64 v127, 0, 1, s[12:13]
	v_lshrrev_b32_e32 v127, v127, v140
	v_cmp_eq_u32_e64 s[14:15], 0, v127
	v_add_u32_e32 v127, 0xfffffe00, v190
	v_mul_hi_i32 v126, v136, s1
	s_cmp_eq_u32 s10, 1
	v_lshrrev_b32_e32 v159, 6, v127
	v_lshrrev_b32_e32 v127, 31, v126
	v_ashrrev_i32_e32 v126, 11, v126
	v_lshlrev_b32_e32 v158, 4, v140
	s_movk_i32 s6, 0x1ff
	s_cselect_b64 s[94:95], -1, 0
	s_movk_i32 s10, 0xff
	s_cmpk_gt_u32 s22, 0x7ff
	v_add_u32_e32 v139, v126, v127
	v_and_b32_e32 v161, 16, v158
	v_cmp_lt_i32_e64 s[6:7], s6, v190
	v_cmp_lt_i32_e64 s[10:11], s10, v190
	s_cselect_b64 s[22:23], -1, 0
	v_ashrrev_i32_e32 v135, 31, v190
	v_mov_b32_e32 v134, v190
	v_mad_i32_i24 v138, v139, s80, v136
	s_and_saveexec_b64 s[30:31], s[16:17]
	s_xor_b64 s[30:31], exec, s[30:31]
	s_cbranch_execz .LBB0_594
	s_and_saveexec_b64 s[52:53], s[2:3]
	s_cbranch_execz .LBB0_593
	s_movk_i32 s45, 0xff
	v_cmp_lt_i32_e32 vcc, s45, v138
	s_and_b64 s[46:47], s[86:87], vcc
	v_mov_b32_e32 v140, v131
	v_mov_b32_e32 v141, v133
	v_mov_b32_e32 v142, v123
	v_mov_b32_e32 v143, v125
	v_mov_b32_e32 v144, v119
	v_mov_b32_e32 v145, v121
	v_mov_b32_e32 v154, v115
	v_mov_b32_e32 v155, v117
	v_mov_b32_e32 v146, v130
	v_mov_b32_e32 v147, v132
	v_mov_b32_e32 v148, v122
	v_mov_b32_e32 v149, v124
	v_mov_b32_e32 v150, v118
	v_mov_b32_e32 v151, v120
	v_mov_b32_e32 v152, v114
	v_mov_b32_e32 v153, v116
	s_and_saveexec_b64 s[54:55], s[46:47]
	s_cbranch_execz .LBB0_571
	v_readlane_b32 s46, v252, 1
	v_cndmask_b32_e64 v128, v238, v240, s[12:13]
	v_mov_b32_e32 v129, v191
	v_readlane_b32 s47, v252, 2
	v_add_u32_e32 v126, 0xffffff00, v138
	v_lshrrev_b32_e32 v126, 6, v126
	v_lshl_add_u64 v[128:129], s[46:47], 0, v[128:129]
	global_load_dwordx2 v[128:129], v[128:129], off
	v_cndmask_b32_e64 v126, v162, v126, s[14:15]
	v_lshlrev_b32_e32 v127, 4, v126
	v_lshl_or_b32 v126, v126, 5, v161
	v_cndmask_b32_e64 v126, v127, v126, s[12:13]
	v_mov_b32_e32 v127, v191
	v_mov_b32_e32 v182, v130
	v_mov_b32_e32 v183, v133
	v_mov_b32_e32 v130, v131
	v_mov_b32_e32 v131, v132
	s_waitcnt vmcnt(0)
	v_lshl_add_u64 v[156:157], v[126:127], 2, v[128:129]
	global_load_dwordx4 v[126:129], v[156:157], off offset:48
	global_load_dwordx4 v[164:167], v[156:157], off offset:32
	global_load_dwordx4 v[168:171], v[156:157], off offset:16
	global_load_dwordx4 v[172:175], v[156:157], off
	s_waitcnt vmcnt(3)
	v_mov_b32_e32 v156, v127
	s_waitcnt vmcnt(2)
	v_mov_b32_e32 v180, v165
	s_waitcnt vmcnt(1)
	v_mov_b32_e32 v178, v169
	s_waitcnt vmcnt(0)
	v_mov_b32_e32 v132, v172
	v_mov_b32_e32 v133, v175
	v_mov_b32_e32 v176, v173
	v_mov_b32_e32 v177, v174
	v_pk_mul_f32 v[130:131], v[130:131], v[132:133]
	v_mov_b32_e32 v132, v173
	v_pk_mul_f32 v[132:133], v[140:141], v[132:133]
	v_pk_fma_f32 v[140:141], v[182:183], v[176:177], v[130:131]
	v_mov_b32_e32 v130, v122
	v_mov_b32_e32 v131, v125
	v_mov_b32_e32 v122, v123
	v_mov_b32_e32 v123, v124
	v_mov_b32_e32 v124, v168
	v_mov_b32_e32 v125, v171
	v_mov_b32_e32 v179, v170
	v_pk_mul_f32 v[122:123], v[122:123], v[124:125]
	v_mov_b32_e32 v124, v169
	v_pk_mul_f32 v[124:125], v[142:143], v[124:125]
	v_pk_fma_f32 v[142:143], v[130:131], v[178:179], v[122:123]
	v_mov_b32_e32 v122, v118
	v_mov_b32_e32 v123, v121
	v_mov_b32_e32 v118, v119
	v_mov_b32_e32 v119, v120
	v_mov_b32_e32 v120, v164
	v_mov_b32_e32 v121, v167
	v_mov_b32_e32 v181, v166
	v_pk_mul_f32 v[118:119], v[118:119], v[120:121]
	v_mov_b32_e32 v120, v165
	v_pk_mul_f32 v[120:121], v[144:145], v[120:121]
	v_pk_fma_f32 v[144:145], v[122:123], v[180:181], v[118:119]
	v_mov_b32_e32 v118, v114
	v_mov_b32_e32 v119, v117
	v_mov_b32_e32 v114, v115
	v_mov_b32_e32 v115, v116
	v_mov_b32_e32 v116, v126
	v_mov_b32_e32 v117, v129
	v_pk_mul_f32 v[114:115], v[114:115], v[116:117]
	v_mov_b32_e32 v116, v127
	v_mov_b32_e32 v157, v128
	v_mov_b32_e32 v173, v174
	v_mov_b32_e32 v169, v170
	v_mov_b32_e32 v165, v166
	v_pk_mul_f32 v[116:117], v[154:155], v[116:117]
	v_mov_b32_e32 v127, v128
	v_pk_fma_f32 v[146:147], v[146:147], v[172:173], v[132:133] neg_lo:[0,0,1] neg_hi:[0,0,1]
	v_pk_fma_f32 v[148:149], v[148:149], v[168:169], v[124:125] neg_lo:[0,0,1] neg_hi:[0,0,1]
	v_pk_fma_f32 v[150:151], v[150:151], v[164:165], v[120:121] neg_lo:[0,0,1] neg_hi:[0,0,1]
	v_pk_fma_f32 v[152:153], v[152:153], v[126:127], v[116:117] neg_lo:[0,0,1] neg_hi:[0,0,1]
	v_pk_fma_f32 v[154:155], v[118:119], v[156:157], v[114:115]
